# layer-1 branch/out weight conversion moved from the prologue phase into layer 1's phase 3 (idle workgroups, non-temporal), prologue phase steps over that tile range
# speedup vs baseline: 1.0021x; 1.0021x over previous
; __device__ __forceinline__ float bfhi(unsigned w) { return __uint_as_float(w & 0xffff0000u); }
; __global__ void __launch_bounds__(512, 2) fwd_megakernel(Params PK) {
;     ...
;         } else if (ph == 3) {
;             { const unsigned* LRW = (const unsigned*)(ws + WS_LRA); float* AGP = (float*)(ws + WS_AGG); float* AGH = AGP + 128 * 1024;
;                 for (size_t id = gtid; id < (size_t)128 * 1024; id += gstride) { const int ch = (int)(id & 1023), bc = (int)(id >> 10); const size_t base = (size_t)bc * 128 * DBR + ch;
;                     float p = 1.f, h = 0.f; const float sc = fmaxf(1.0f - __expf(-((const float*)(ws + WS_PEW1))[512 + ch]), 1e-30f) * (1.0f / 65535.0f);
; #pragma unroll 8
;                     for (int t = 0; t < 128; ++t) { const unsigned w = LRW[base + (size_t)t * DBR]; const float a = 1.0f - (float)(w & 0xffffu) * sc, g = bfhi(w); p *= a; h = a * h + g; }
;                     AGP[id] = p; AGH[id] = h; } }
;             { pg8::SchedCmp1 S{bid, (const bf16_t*)(ws + WS_A0), (const bf16_t*)(ws + WS_W1T)}; pg8::EpiBf16 E{(bf16_t*)(ws + WS_HID), 256, (size_t)4096 * 256, (const float*)(ws + WS_PEW1), 256, 2}; pg8::gemm_phase(lds, 2048, S, E); }
.Lp3_tc:
	s_cmp_lt_u32 s2, 32
	s_cbranch_scc1 .LBB0_786
	s_cmp_eq_u32 s70, 11
	s_cbranch_scc1 .Lp11_tc_go
	s_cmp_lg_u32 s70, 3
	s_cbranch_scc1 .LBB0_786

; __device__ __forceinline__ void prologue(LAS unsigned char* lds, const Ctx& P, int l) {
;     ...
;         if (q < T_IN) { const int kt = q & 31, ntl = q >> 5; tconv_tile(tile, P.in[3] + (size_t)l * DM * INW, INW, kt * 64, ntl * 64, 1, (bf16_t*)(ws + WS_WIN), DM); continue; }
;         q -= T_IN;
;         if (q < T_BR) { const int br = q >> 9, r = q & 511, kt = r & 15, ntl = r >> 4;
;             tconv_tile(tile, P.in[23] + ((size_t)l * 4 + br) * DBR * DM, DM, kt * 64, ntl * 64, 0, (bf16_t*)(ws + WS_WBR) + (size_t)br * DM * DBR, DBR); continue; }
;         q -= T_BR;
;         if (q < T_OUT) { const int kt = q & 31, ntl = q >> 5; tconv_tile(tile, P.in[24] + (size_t)l * DM * DM, DM, kt * 64, ntl * 64, 0, (bf16_t*)(ws + WS_WOUT), DM); continue; }
.Lp11_tc_go:
	v_mov_b32_e32 v26, 0x23f00
	ds_read_b64 v[34:35], v26 offset:24
	ds_read_b64 v[36:37], v26 offset:184
	ds_read_b64 v[38:39], v26 offset:192
	ds_read_b64 v[40:41], v26 offset:176
	ds_read_b64 v[42:43], v26 offset:136
	ds_read_b64 v[44:45], v26 offset:144
	ds_read_b64 v[46:47], v26 offset:80
	ds_read_b64 v[48:49], v26 offset:96
	s_waitcnt lgkmcnt(0)
	v_readfirstlane_b32 s4, v34
	v_readfirstlane_b32 s5, v35
	v_readfirstlane_b32 s6, v36
	v_readfirstlane_b32 s7, v37
	v_readfirstlane_b32 s8, v38
	v_readfirstlane_b32 s9, v39
	v_readfirstlane_b32 s10, v40
	v_readfirstlane_b32 s11, v41
	v_readfirstlane_b32 s12, v42
	v_readfirstlane_b32 s13, v43
	v_readfirstlane_b32 s14, v44
	v_readfirstlane_b32 s15, v45
	v_readfirstlane_b32 s16, v46
	v_readfirstlane_b32 s17, v47
	v_readfirstlane_b32 s18, v48
	v_readfirstlane_b32 s19, v49
	s_nop 3
	s_add_u32 s4, s4, 0x9460000
	s_addc_u32 s5, s5, 0
	s_add_u32 s6, s6, 0x2000000
	s_addc_u32 s7, s7, 0
	s_add_u32 s8, s8, 0x1000000
	s_addc_u32 s9, s9, 0
	s_add_u32 s10, s10, 0x1000000
	s_addc_u32 s11, s11, 0
	s_add_u32 s12, s12, 0x200000
	s_addc_u32 s13, s13, 0
	s_add_u32 s14, s14, 0x200000
	s_addc_u32 s15, s15, 0
	s_add_u32 s16, s16, 0x80000
	s_addc_u32 s17, s17, 0
	s_add_u32 s18, s18, 0x80000
	s_addc_u32 s19, s19, 0
	v_lshrrev_b32_e32 v20, 4, v234
	v_and_b32_e32 v21, 15, v234
	v_lshlrev_b32_e32 v21, 2, v21
	v_mul_u32_u24_e32 v22, 0x104, v20
	v_lshl_add_u32 v22, v21, 2, v22
	v_lshrrev_b32_e32 v24, 3, v234
	v_and_b32_e32 v25, 7, v234
	v_lshlrev_b32_e32 v25, 3, v25
	v_mul_u32_u24_e32 v23, 0x104, v25
	v_lshl_add_u32 v23, v24, 2, v23
	s_add_u32 s24, s2, 9568
	s_mov_b32 s25, s24
	s_min_u32 s0, s24, 12671
	s_mov_b32 s21, s0
	s_mov_b32 s0, s21
	s_cmpk_lt_u32 s0, 9600
	s_cbranch_scc0 .Ltc3_c2
	s_and_b32 s1, s0, 31
	s_lshl_b32 s1, s1, 6
	s_lshr_b32 s21, s0, 5
	s_lshl_b32 s21, s21, 6
	s_movk_i32 s29, 64
	s_cmpk_lt_u32 s21, 7680
	s_cbranch_scc1 .Ltc3_n4
	s_cmpk_lt_u32 s21, 18944
	s_cbranch_scc0 .Ltc3_t3
	s_add_u32 s21, s21, 48
	s_branch .Ltc3_n4

; __device__ __forceinline__ void tconv_tile(LAS float* tile, const float* src, int ld, int k0, int n0, int mode, bf16_t* dst, int K) {
;     ...
;     for (int it = 0; it < 2; ++it) { const int idx = tid + it * 512, kk = idx >> 4, n4 = (idx & 15) * 4, nn = n0 + n4; int oc = nn; bool valid = true;
;         if (mode == 1) { if (nn < 7680) oc = nn; else if (nn < 18944) oc = nn + 48; else if (nn < INW) oc = 7680 + (nn - 18944); else valid = false; }
;         f32x4 v = (f32x4){0.f, 0.f, 0.f, 0.f}; if (valid) v = *(const f32x4*)(src + (size_t)(k0 + kk) * ld + oc);
; __device__ __forceinline__ void prologue(LAS unsigned char* lds, const Ctx& P, int l) {
;     ...
;         if (q < T_BR) { const int br = q >> 9, r = q & 511, kt = r & 15, ntl = r >> 4;
;             tconv_tile(tile, P.in[23] + ((size_t)l * 4 + br) * DBR * DM, DM, kt * 64, ntl * 64, 0, (bf16_t*)(ws + WS_WBR) + (size_t)br * DM * DBR, DBR); continue; }
;         q -= T_BR;
;         if (q < T_OUT) { const int kt = q & 31, ntl = q >> 5; tconv_tile(tile, P.in[24] + (size_t)l * DM * DM, DM, kt * 64, ntl * 64, 0, (bf16_t*)(ws + WS_WOUT), DM); continue; }
.Ltc3_d1:
	v_mov_b32_e32 v34, 0
	v_mov_b32_e32 v35, 0
	v_mov_b32_e32 v36, 0
	v_mov_b32_e32 v37, 0
	v_mov_b32_e32 v38, 0
	v_mov_b32_e32 v39, 0
	v_mov_b32_e32 v40, 0
	v_mov_b32_e32 v41, 0
	v_mul_u32_u24_e32 v26, s28, v20
	v_add_lshl_u32 v26, v26, v21, 2
	s_lshl_b32 s0, s28, 7
	v_add_u32_e32 v27, s0, v26
	v_cmp_gt_i32_e32 vcc, s29, v21
	s_and_saveexec_b64 s[0:1], vcc
	global_load_dwordx4 v[34:37], v26, s[26:27] nt
	global_load_dwordx4 v[38:41], v27, s[26:27] nt
	s_mov_b64 exec, s[0:1]
	s_add_u32 s24, s24, 0xe0
	s_min_u32 s0, s24, 12671
	s_mov_b32 s21, s0
	s_mov_b32 s0, s21
	s_cmpk_lt_u32 s0, 9600
	s_cbranch_scc0 .Ltc3_c15
	s_and_b32 s1, s0, 31
	s_lshl_b32 s1, s1, 6
	s_lshr_b32 s21, s0, 5
	s_lshl_b32 s21, s21, 6
	s_movk_i32 s29, 64
	s_cmpk_lt_u32 s21, 7680
	s_cbranch_scc1 .Ltc3_n17
	s_cmpk_lt_u32 s21, 18944
	s_cbranch_scc0 .Ltc3_t16
	s_add_u32 s21, s21, 48
	s_branch .Ltc3_n17

; __device__ __forceinline__ void tconv_tile(LAS float* tile, const float* src, int ld, int k0, int n0, int mode, bf16_t* dst, int K) {
;     ...
;     for (int it = 0; it < 2; ++it) { const int idx = tid + it * 512, kk = idx >> 4, n4 = (idx & 15) * 4, nn = n0 + n4; int oc = nn; bool valid = true;
;         if (mode == 1) { if (nn < 7680) oc = nn; else if (nn < 18944) oc = nn + 48; else if (nn < INW) oc = 7680 + (nn - 18944); else valid = false; }
;         f32x4 v = (f32x4){0.f, 0.f, 0.f, 0.f}; if (valid) v = *(const f32x4*)(src + (size_t)(k0 + kk) * ld + oc);
; __device__ __forceinline__ void prologue(LAS unsigned char* lds, const Ctx& P, int l) {
;     ...
;         if (q < T_BR) { const int br = q >> 9, r = q & 511, kt = r & 15, ntl = r >> 4;
;             tconv_tile(tile, P.in[23] + ((size_t)l * 4 + br) * DBR * DM, DM, kt * 64, ntl * 64, 0, (bf16_t*)(ws + WS_WBR) + (size_t)br * DM * DBR, DBR); continue; }
;         q -= T_BR;
;         if (q < T_OUT) { const int kt = q & 31, ntl = q >> 5; tconv_tile(tile, P.in[24] + (size_t)l * DM * DM, DM, kt * 64, ntl * 64, 0, (bf16_t*)(ws + WS_WOUT), DM); continue; }
.Ltc3_d14:
	v_mov_b32_e32 v42, 0
	v_mov_b32_e32 v43, 0
	v_mov_b32_e32 v44, 0
	v_mov_b32_e32 v45, 0
	v_mov_b32_e32 v46, 0
	v_mov_b32_e32 v47, 0
	v_mov_b32_e32 v48, 0
	v_mov_b32_e32 v49, 0
	v_mul_u32_u24_e32 v26, s28, v20
	v_add_lshl_u32 v26, v26, v21, 2
	s_lshl_b32 s0, s28, 7
	v_add_u32_e32 v27, s0, v26
	v_cmp_gt_i32_e32 vcc, s29, v21
	s_and_saveexec_b64 s[0:1], vcc
	global_load_dwordx4 v[42:45], v26, s[26:27] nt
	global_load_dwordx4 v[46:49], v27, s[26:27] nt
	s_mov_b64 exec, s[0:1]
	s_add_u32 s24, s24, 0xe0
	s_min_u32 s0, s24, 12671
	s_mov_b32 s21, s0
	s_mov_b32 s0, s21
	s_cmpk_lt_u32 s0, 9600
	s_cbranch_scc0 .Ltc3_c28
	s_and_b32 s1, s0, 31
	s_lshl_b32 s1, s1, 6
	s_lshr_b32 s21, s0, 5
	s_lshl_b32 s21, s21, 6
	s_movk_i32 s29, 64
	s_cmpk_lt_u32 s21, 7680
	s_cbranch_scc1 .Ltc3_n30
	s_cmpk_lt_u32 s21, 18944
	s_cbranch_scc0 .Ltc3_t29
	s_add_u32 s21, s21, 48
	s_branch .Ltc3_n30

; __device__ __forceinline__ void tconv_tile(LAS float* tile, const float* src, int ld, int k0, int n0, int mode, bf16_t* dst, int K) {
;     ...
;     for (int it = 0; it < 2; ++it) { const int idx = tid + it * 512, kk = idx >> 4, n4 = (idx & 15) * 4, nn = n0 + n4; int oc = nn; bool valid = true;
;         if (mode == 1) { if (nn < 7680) oc = nn; else if (nn < 18944) oc = nn + 48; else if (nn < INW) oc = 7680 + (nn - 18944); else valid = false; }
;         f32x4 v = (f32x4){0.f, 0.f, 0.f, 0.f}; if (valid) v = *(const f32x4*)(src + (size_t)(k0 + kk) * ld + oc);
; __device__ __forceinline__ void prologue(LAS unsigned char* lds, const Ctx& P, int l) {
;     ...
;         if (q < T_BR) { const int br = q >> 9, r = q & 511, kt = r & 15, ntl = r >> 4;
;             tconv_tile(tile, P.in[23] + ((size_t)l * 4 + br) * DBR * DM, DM, kt * 64, ntl * 64, 0, (bf16_t*)(ws + WS_WBR) + (size_t)br * DM * DBR, DBR); continue; }
;         q -= T_BR;
;         if (q < T_OUT) { const int kt = q & 31, ntl = q >> 5; tconv_tile(tile, P.in[24] + (size_t)l * DM * DM, DM, kt * 64, ntl * 64, 0, (bf16_t*)(ws + WS_WOUT), DM); continue; }
.Ltc3_d27:
	v_mov_b32_e32 v50, 0
	v_mov_b32_e32 v51, 0
	v_mov_b32_e32 v52, 0
	v_mov_b32_e32 v53, 0
	v_mov_b32_e32 v54, 0
	v_mov_b32_e32 v55, 0
	v_mov_b32_e32 v56, 0
	v_mov_b32_e32 v57, 0
	v_mul_u32_u24_e32 v26, s28, v20
	v_add_lshl_u32 v26, v26, v21, 2
	s_lshl_b32 s0, s28, 7
	v_add_u32_e32 v27, s0, v26
	v_cmp_gt_i32_e32 vcc, s29, v21
	s_and_saveexec_b64 s[0:1], vcc
	global_load_dwordx4 v[50:53], v26, s[26:27] nt
	global_load_dwordx4 v[54:57], v27, s[26:27] nt
	s_mov_b64 exec, s[0:1]
	s_add_u32 s24, s24, 0xe0
	s_min_u32 s0, s24, 12671
	s_mov_b32 s21, s0
	s_mov_b32 s0, s21
	s_cmpk_lt_u32 s0, 9600
	s_cbranch_scc0 .Ltc3_c41
	s_and_b32 s1, s0, 31
	s_lshl_b32 s1, s1, 6
	s_lshr_b32 s21, s0, 5
	s_lshl_b32 s21, s21, 6
	s_movk_i32 s29, 64
	s_cmpk_lt_u32 s21, 7680
	s_cbranch_scc1 .Ltc3_n43
	s_cmpk_lt_u32 s21, 18944
	s_cbranch_scc0 .Ltc3_t42
	s_add_u32 s21, s21, 48
	s_branch .Ltc3_n43

; __device__ __forceinline__ void tconv_tile(LAS float* tile, const float* src, int ld, int k0, int n0, int mode, bf16_t* dst, int K) {
;     ...
;     for (int it = 0; it < 2; ++it) { const int idx = tid + it * 512, kk = idx >> 4, n4 = (idx & 15) * 4, nn = n0 + n4; int oc = nn; bool valid = true;
;         if (mode == 1) { if (nn < 7680) oc = nn; else if (nn < 18944) oc = nn + 48; else if (nn < INW) oc = 7680 + (nn - 18944); else valid = false; }
;         f32x4 v = (f32x4){0.f, 0.f, 0.f, 0.f}; if (valid) v = *(const f32x4*)(src + (size_t)(k0 + kk) * ld + oc);
; __device__ __forceinline__ void prologue(LAS unsigned char* lds, const Ctx& P, int l) {
;     ...
;         if (q < T_BR) { const int br = q >> 9, r = q & 511, kt = r & 15, ntl = r >> 4;
;             tconv_tile(tile, P.in[23] + ((size_t)l * 4 + br) * DBR * DM, DM, kt * 64, ntl * 64, 0, (bf16_t*)(ws + WS_WBR) + (size_t)br * DM * DBR, DBR); continue; }
;         q -= T_BR;
;         if (q < T_OUT) { const int kt = q & 31, ntl = q >> 5; tconv_tile(tile, P.in[24] + (size_t)l * DM * DM, DM, kt * 64, ntl * 64, 0, (bf16_t*)(ws + WS_WOUT), DM); continue; }
.Ltc3_d40:
	v_mov_b32_e32 v58, 0
	v_mov_b32_e32 v59, 0
	v_mov_b32_e32 v60, 0
	v_mov_b32_e32 v61, 0
	v_mov_b32_e32 v62, 0
	v_mov_b32_e32 v63, 0
	v_mov_b32_e32 v64, 0
	v_mov_b32_e32 v65, 0
	v_mul_u32_u24_e32 v26, s28, v20
	v_add_lshl_u32 v26, v26, v21, 2
	s_lshl_b32 s0, s28, 7
	v_add_u32_e32 v27, s0, v26
	v_cmp_gt_i32_e32 vcc, s29, v21
	s_and_saveexec_b64 s[0:1], vcc
	global_load_dwordx4 v[58:61], v26, s[26:27] nt
	global_load_dwordx4 v[62:65], v27, s[26:27] nt
	s_mov_b64 exec, s[0:1]
	s_add_u32 s24, s24, 0xe0
	s_min_u32 s0, s24, 12671
	s_mov_b32 s21, s0
	s_mov_b32 s0, s21
	s_cmpk_lt_u32 s0, 9600
	s_cbranch_scc0 .Ltc3_c54
	s_and_b32 s1, s0, 31
	s_lshl_b32 s1, s1, 6
	s_lshr_b32 s21, s0, 5
	s_lshl_b32 s21, s21, 6
	s_movk_i32 s29, 64
	s_cmpk_lt_u32 s21, 7680
	s_cbranch_scc1 .Ltc3_n56
	s_cmpk_lt_u32 s21, 18944
	s_cbranch_scc0 .Ltc3_t55
	s_add_u32 s21, s21, 48
	s_branch .Ltc3_n56

; __device__ __forceinline__ void tconv_tile(LAS float* tile, const float* src, int ld, int k0, int n0, int mode, bf16_t* dst, int K) {
;     ...
;     for (int it = 0; it < 2; ++it) { const int idx = tid + it * 512, kk = idx >> 4, n4 = (idx & 15) * 4, nn = n0 + n4; int oc = nn; bool valid = true;
;         if (mode == 1) { if (nn < 7680) oc = nn; else if (nn < 18944) oc = nn + 48; else if (nn < INW) oc = 7680 + (nn - 18944); else valid = false; }
;         f32x4 v = (f32x4){0.f, 0.f, 0.f, 0.f}; if (valid) v = *(const f32x4*)(src + (size_t)(k0 + kk) * ld + oc);
; __device__ __forceinline__ void prologue(LAS unsigned char* lds, const Ctx& P, int l) {
;     ...
;         if (q < T_BR) { const int br = q >> 9, r = q & 511, kt = r & 15, ntl = r >> 4;
;             tconv_tile(tile, P.in[23] + ((size_t)l * 4 + br) * DBR * DM, DM, kt * 64, ntl * 64, 0, (bf16_t*)(ws + WS_WBR) + (size_t)br * DM * DBR, DBR); continue; }
;         q -= T_BR;
;         if (q < T_OUT) { const int kt = q & 31, ntl = q >> 5; tconv_tile(tile, P.in[24] + (size_t)l * DM * DM, DM, kt * 64, ntl * 64, 0, (bf16_t*)(ws + WS_WOUT), DM); continue; }
.Ltc3_d53:
	v_mov_b32_e32 v78, 0
	v_mov_b32_e32 v79, 0
	v_mov_b32_e32 v80, 0
	v_mov_b32_e32 v81, 0
	v_mov_b32_e32 v82, 0
	v_mov_b32_e32 v83, 0
	v_mov_b32_e32 v84, 0
	v_mov_b32_e32 v85, 0
	v_mul_u32_u24_e32 v26, s28, v20
	v_add_lshl_u32 v26, v26, v21, 2
	s_lshl_b32 s0, s28, 7
	v_add_u32_e32 v27, s0, v26
	v_cmp_gt_i32_e32 vcc, s29, v21
	s_and_saveexec_b64 s[0:1], vcc
	global_load_dwordx4 v[78:81], v26, s[26:27] nt
	global_load_dwordx4 v[82:85], v27, s[26:27] nt
	s_mov_b64 exec, s[0:1]
	s_add_u32 s24, s24, 0xe0
	s_min_u32 s0, s24, 12671
	s_mov_b32 s21, s0
	s_mov_b32 s0, s21
	s_cmpk_lt_u32 s0, 9600
	s_cbranch_scc0 .Ltc3_c67
	s_and_b32 s1, s0, 31
	s_lshl_b32 s1, s1, 6
	s_lshr_b32 s21, s0, 5
	s_lshl_b32 s21, s21, 6
	s_movk_i32 s29, 64
	s_cmpk_lt_u32 s21, 7680
	s_cbranch_scc1 .Ltc3_n69
	s_cmpk_lt_u32 s21, 18944
	s_cbranch_scc0 .Ltc3_t68
	s_add_u32 s21, s21, 48
	s_branch .Ltc3_n69

; __device__ __forceinline__ unsigned cvt_pk_bf16(float lo, float hi) { unsigned r; asm("v_cvt_pk_bf16_f32 %0, %1, %2" : "=v"(r) : "v"(lo), "v"(hi)); return r; }
; __device__ __forceinline__ void tconv_tile(LAS float* tile, const float* src, int ld, int k0, int n0, int mode, bf16_t* dst, int K) {
;     ...
;     for (int it = 0; it < 2; ++it) { const int idx = tid + it * 512, kk = idx >> 4, n4 = (idx & 15) * 4, nn = n0 + n4; int oc = nn; bool valid = true;
;         if (mode == 1) { if (nn < 7680) oc = nn; else if (nn < 18944) oc = nn + 48; else if (nn < INW) oc = 7680 + (nn - 18944); else valid = false; }
;         f32x4 v = (f32x4){0.f, 0.f, 0.f, 0.f}; if (valid) v = *(const f32x4*)(src + (size_t)(k0 + kk) * ld + oc);
;         tile[kk * 65 + n4 + 0] = v[0]; tile[kk * 65 + n4 + 1] = v[1]; tile[kk * 65 + n4 + 2] = v[2]; tile[kk * 65 + n4 + 3] = v[3]; }
;     __syncthreads();
;     { const int n = tid >> 3, k8 = (tid & 7) * 8; float v[8];
; #pragma unroll
;         for (int e = 0; e < 8; ++e) v[e] = tile[(k8 + e) * 65 + n];
;         u32x4 w; w.x = cvt_pk_bf16(v[0], v[1]); w.y = cvt_pk_bf16(v[2], v[3]); w.z = cvt_pk_bf16(v[4], v[5]); w.w = cvt_pk_bf16(v[6], v[7]);
;         *(u32x4*)(dst + (size_t)(n0 + n) * K + k0 + k8) = w; }
; __device__ __forceinline__ void prologue(LAS unsigned char* lds, const Ctx& P, int l) {
;     ...
;         if (q < T_BR) { const int br = q >> 9, r = q & 511, kt = r & 15, ntl = r >> 4;
;             tconv_tile(tile, P.in[23] + ((size_t)l * 4 + br) * DBR * DM, DM, kt * 64, ntl * 64, 0, (bf16_t*)(ws + WS_WBR) + (size_t)br * DM * DBR, DBR); continue; }
;         q -= T_BR;
;         if (q < T_OUT) { const int kt = q & 31, ntl = q >> 5; tconv_tile(tile, P.in[24] + (size_t)l * DM * DM, DM, kt * 64, ntl * 64, 0, (bf16_t*)(ws + WS_WOUT), DM); continue; }
.Ltc3_d66:
	v_mov_b32_e32 v86, 0
	v_mov_b32_e32 v87, 0
	v_mov_b32_e32 v88, 0
	v_mov_b32_e32 v89, 0
	v_mov_b32_e32 v90, 0
	v_mov_b32_e32 v91, 0
	v_mov_b32_e32 v92, 0
	v_mov_b32_e32 v93, 0
	v_mul_u32_u24_e32 v26, s28, v20
	v_add_lshl_u32 v26, v26, v21, 2
	s_lshl_b32 s0, s28, 7
	v_add_u32_e32 v27, s0, v26
	v_cmp_gt_i32_e32 vcc, s29, v21
	s_and_saveexec_b64 s[0:1], vcc
	global_load_dwordx4 v[86:89], v26, s[26:27] nt
	global_load_dwordx4 v[90:93], v27, s[26:27] nt
	s_mov_b64 exec, s[0:1]
	s_add_u32 s24, s24, 0xe0
	s_cmpk_ge_u32 s25, 12672
	s_cbranch_scc1 .Ltc3_exit
	s_waitcnt vmcnt(10)
	v_add_u32_e32 v28, 0, v22
	ds_write2_b32 v28, v34, v35 offset1:1
	ds_write2_b32 v28, v36, v37 offset0:2 offset1:3
	v_add_u32_e32 v28, 0x2080, v28
	ds_write2_b32 v28, v38, v39 offset1:1
	ds_write2_b32 v28, v40, v41 offset0:2 offset1:3
	s_mov_b32 s21, s25
	s_mov_b32 s0, s21
	s_cmpk_lt_u32 s0, 9600
	s_cbranch_scc0 .Ltc3_c80
	s_and_b32 s1, s0, 31
	s_lshl_b32 s1, s1, 6
	s_lshr_b32 s21, s0, 5
	s_lshl_b32 s21, s21, 17
	s_add_u32 s1, s1, s21
	s_lshl_b32 s1, s1, 1
	s_add_u32 s1, s1, 0x4001000
	s_add_u32 s30, s68, s1
	s_addc_u32 s31, s69, 0
	s_movk_i32 s20, 0x800
	s_branch .Ltc3_d79

; __device__ __forceinline__ unsigned cvt_pk_bf16(float lo, float hi) { unsigned r; asm("v_cvt_pk_bf16_f32 %0, %1, %2" : "=v"(r) : "v"(lo), "v"(hi)); return r; }
; __device__ __forceinline__ void tconv_tile(LAS float* tile, const float* src, int ld, int k0, int n0, int mode, bf16_t* dst, int K) {
;     ...
;     for (int it = 0; it < 2; ++it) { const int idx = tid + it * 512, kk = idx >> 4, n4 = (idx & 15) * 4, nn = n0 + n4; int oc = nn; bool valid = true;
;         if (mode == 1) { if (nn < 7680) oc = nn; else if (nn < 18944) oc = nn + 48; else if (nn < INW) oc = 7680 + (nn - 18944); else valid = false; }
;         f32x4 v = (f32x4){0.f, 0.f, 0.f, 0.f}; if (valid) v = *(const f32x4*)(src + (size_t)(k0 + kk) * ld + oc);
;         tile[kk * 65 + n4 + 0] = v[0]; tile[kk * 65 + n4 + 1] = v[1]; tile[kk * 65 + n4 + 2] = v[2]; tile[kk * 65 + n4 + 3] = v[3]; }
;     __syncthreads();
;     { const int n = tid >> 3, k8 = (tid & 7) * 8; float v[8];
; #pragma unroll
;         for (int e = 0; e < 8; ++e) v[e] = tile[(k8 + e) * 65 + n];
;         u32x4 w; w.x = cvt_pk_bf16(v[0], v[1]); w.y = cvt_pk_bf16(v[2], v[3]); w.z = cvt_pk_bf16(v[4], v[5]); w.w = cvt_pk_bf16(v[6], v[7]);
;         *(u32x4*)(dst + (size_t)(n0 + n) * K + k0 + k8) = w; }
.Ltc3_d79:
	v_mul_u32_u24_e32 v29, s20, v24
	v_add_lshl_u32 v29, v29, v25, 1
	s_waitcnt lgkmcnt(0)
	s_barrier
	v_add_u32_e32 v28, 0, v23
	ds_read2_b32 v[2:3], v28 offset1:65
	ds_read2_b32 v[4:5], v28 offset0:130 offset1:195
	v_add_u32_e32 v28, 0x400, v28
	ds_read2_b32 v[6:7], v28 offset0:4 offset1:69
	ds_read2_b32 v[10:11], v28 offset0:134 offset1:199
	s_waitcnt lgkmcnt(3)
	v_cvt_pk_bf16_f32 v2, v2, v3
	s_waitcnt lgkmcnt(2)
	v_cvt_pk_bf16_f32 v3, v4, v5
	s_waitcnt lgkmcnt(1)
	v_cvt_pk_bf16_f32 v4, v6, v7
	s_waitcnt lgkmcnt(0)
	v_cvt_pk_bf16_f32 v5, v10, v11
	global_store_dwordx4 v29, v[2:5], s[30:31] nt
	s_add_u32 s25, s25, 0xe0
	s_min_u32 s0, s24, 12671
	s_mov_b32 s21, s0
	s_mov_b32 s0, s21
	s_cmpk_lt_u32 s0, 9600
	s_cbranch_scc0 .Ltc3_c87
	s_and_b32 s1, s0, 31
	s_lshl_b32 s1, s1, 6
	s_lshr_b32 s21, s0, 5
	s_lshl_b32 s21, s21, 6
	s_movk_i32 s29, 64
	s_cmpk_lt_u32 s21, 7680
	s_cbranch_scc1 .Ltc3_n89
	s_cmpk_lt_u32 s21, 18944
	s_cbranch_scc0 .Ltc3_t88
	s_add_u32 s21, s21, 48
	s_branch .Ltc3_n89

; __device__ __forceinline__ unsigned cvt_pk_bf16(float lo, float hi) { unsigned r; asm("v_cvt_pk_bf16_f32 %0, %1, %2" : "=v"(r) : "v"(lo), "v"(hi)); return r; }
; __device__ __forceinline__ void tconv_tile(LAS float* tile, const float* src, int ld, int k0, int n0, int mode, bf16_t* dst, int K) {
;     ...
;     for (int it = 0; it < 2; ++it) { const int idx = tid + it * 512, kk = idx >> 4, n4 = (idx & 15) * 4, nn = n0 + n4; int oc = nn; bool valid = true;
;         if (mode == 1) { if (nn < 7680) oc = nn; else if (nn < 18944) oc = nn + 48; else if (nn < INW) oc = 7680 + (nn - 18944); else valid = false; }
;         f32x4 v = (f32x4){0.f, 0.f, 0.f, 0.f}; if (valid) v = *(const f32x4*)(src + (size_t)(k0 + kk) * ld + oc);
;         tile[kk * 65 + n4 + 0] = v[0]; tile[kk * 65 + n4 + 1] = v[1]; tile[kk * 65 + n4 + 2] = v[2]; tile[kk * 65 + n4 + 3] = v[3]; }
;     __syncthreads();
;     { const int n = tid >> 3, k8 = (tid & 7) * 8; float v[8];
; #pragma unroll
;         for (int e = 0; e < 8; ++e) v[e] = tile[(k8 + e) * 65 + n];
;         u32x4 w; w.x = cvt_pk_bf16(v[0], v[1]); w.y = cvt_pk_bf16(v[2], v[3]); w.z = cvt_pk_bf16(v[4], v[5]); w.w = cvt_pk_bf16(v[6], v[7]);
;         *(u32x4*)(dst + (size_t)(n0 + n) * K + k0 + k8) = w; }
; __device__ __forceinline__ void prologue(LAS unsigned char* lds, const Ctx& P, int l) {
;     ...
;         if (q < T_BR) { const int br = q >> 9, r = q & 511, kt = r & 15, ntl = r >> 4;
;             tconv_tile(tile, P.in[23] + ((size_t)l * 4 + br) * DBR * DM, DM, kt * 64, ntl * 64, 0, (bf16_t*)(ws + WS_WBR) + (size_t)br * DM * DBR, DBR); continue; }
;         q -= T_BR;
;         if (q < T_OUT) { const int kt = q & 31, ntl = q >> 5; tconv_tile(tile, P.in[24] + (size_t)l * DM * DM, DM, kt * 64, ntl * 64, 0, (bf16_t*)(ws + WS_WOUT), DM); continue; }
.Ltc3_d86:
	v_mov_b32_e32 v34, 0
	v_mov_b32_e32 v35, 0
	v_mov_b32_e32 v36, 0
	v_mov_b32_e32 v37, 0
	v_mov_b32_e32 v38, 0
	v_mov_b32_e32 v39, 0
	v_mov_b32_e32 v40, 0
	v_mov_b32_e32 v41, 0
	v_mul_u32_u24_e32 v26, s28, v20
	v_add_lshl_u32 v26, v26, v21, 2
	s_lshl_b32 s0, s28, 7
	v_add_u32_e32 v27, s0, v26
	v_cmp_gt_i32_e32 vcc, s29, v21
	s_and_saveexec_b64 s[0:1], vcc
	global_load_dwordx4 v[34:37], v26, s[26:27] nt
	global_load_dwordx4 v[38:41], v27, s[26:27] nt
	s_mov_b64 exec, s[0:1]
	s_add_u32 s24, s24, 0xe0
	s_cmpk_ge_u32 s25, 12672
	s_cbranch_scc1 .Ltc3_exit
	s_waitcnt vmcnt(11)
	v_add_u32_e32 v28, 16896, v22
	ds_write2_b32 v28, v42, v43 offset1:1
	ds_write2_b32 v28, v44, v45 offset0:2 offset1:3
	v_add_u32_e32 v28, 0x2080, v28
	ds_write2_b32 v28, v46, v47 offset1:1
	ds_write2_b32 v28, v48, v49 offset0:2 offset1:3
	s_mov_b32 s21, s25
	s_mov_b32 s0, s21
	s_cmpk_lt_u32 s0, 9600
	s_cbranch_scc0 .Ltc3_c100
	s_and_b32 s1, s0, 31
	s_lshl_b32 s1, s1, 6
	s_lshr_b32 s21, s0, 5
	s_lshl_b32 s21, s21, 17
	s_add_u32 s1, s1, s21
	s_lshl_b32 s1, s1, 1
	s_add_u32 s1, s1, 0x4001000
	s_add_u32 s30, s68, s1
	s_addc_u32 s31, s69, 0
	s_movk_i32 s20, 0x800
	s_branch .Ltc3_d99

; __device__ __forceinline__ unsigned cvt_pk_bf16(float lo, float hi) { unsigned r; asm("v_cvt_pk_bf16_f32 %0, %1, %2" : "=v"(r) : "v"(lo), "v"(hi)); return r; }
; __device__ __forceinline__ void tconv_tile(LAS float* tile, const float* src, int ld, int k0, int n0, int mode, bf16_t* dst, int K) {
;     ...
;     for (int it = 0; it < 2; ++it) { const int idx = tid + it * 512, kk = idx >> 4, n4 = (idx & 15) * 4, nn = n0 + n4; int oc = nn; bool valid = true;
;         if (mode == 1) { if (nn < 7680) oc = nn; else if (nn < 18944) oc = nn + 48; else if (nn < INW) oc = 7680 + (nn - 18944); else valid = false; }
;         f32x4 v = (f32x4){0.f, 0.f, 0.f, 0.f}; if (valid) v = *(const f32x4*)(src + (size_t)(k0 + kk) * ld + oc);
;         tile[kk * 65 + n4 + 0] = v[0]; tile[kk * 65 + n4 + 1] = v[1]; tile[kk * 65 + n4 + 2] = v[2]; tile[kk * 65 + n4 + 3] = v[3]; }
;     __syncthreads();
;     { const int n = tid >> 3, k8 = (tid & 7) * 8; float v[8];
; #pragma unroll
;         for (int e = 0; e < 8; ++e) v[e] = tile[(k8 + e) * 65 + n];
;         u32x4 w; w.x = cvt_pk_bf16(v[0], v[1]); w.y = cvt_pk_bf16(v[2], v[3]); w.z = cvt_pk_bf16(v[4], v[5]); w.w = cvt_pk_bf16(v[6], v[7]);
;         *(u32x4*)(dst + (size_t)(n0 + n) * K + k0 + k8) = w; }
.Ltc3_d99:
	v_mul_u32_u24_e32 v29, s20, v24
	v_add_lshl_u32 v29, v29, v25, 1
	s_waitcnt lgkmcnt(0)
	s_barrier
	v_add_u32_e32 v28, 16896, v23
	ds_read2_b32 v[2:3], v28 offset1:65
	ds_read2_b32 v[4:5], v28 offset0:130 offset1:195
	v_add_u32_e32 v28, 0x400, v28
	ds_read2_b32 v[6:7], v28 offset0:4 offset1:69
	ds_read2_b32 v[10:11], v28 offset0:134 offset1:199
	s_waitcnt lgkmcnt(3)
	v_cvt_pk_bf16_f32 v2, v2, v3
	s_waitcnt lgkmcnt(2)
	v_cvt_pk_bf16_f32 v3, v4, v5
	s_waitcnt lgkmcnt(1)
	v_cvt_pk_bf16_f32 v4, v6, v7
	s_waitcnt lgkmcnt(0)
	v_cvt_pk_bf16_f32 v5, v10, v11
	global_store_dwordx4 v29, v[2:5], s[30:31] nt
	s_add_u32 s25, s25, 0xe0
	s_min_u32 s0, s24, 12671
	s_mov_b32 s21, s0
	s_mov_b32 s0, s21
	s_cmpk_lt_u32 s0, 9600
	s_cbranch_scc0 .Ltc3_c107
	s_and_b32 s1, s0, 31
	s_lshl_b32 s1, s1, 6
	s_lshr_b32 s21, s0, 5
	s_lshl_b32 s21, s21, 6
	s_movk_i32 s29, 64
	s_cmpk_lt_u32 s21, 7680
	s_cbranch_scc1 .Ltc3_n109
	s_cmpk_lt_u32 s21, 18944
	s_cbranch_scc0 .Ltc3_t108
	s_add_u32 s21, s21, 48
	s_branch .Ltc3_n109

; __device__ __forceinline__ unsigned cvt_pk_bf16(float lo, float hi) { unsigned r; asm("v_cvt_pk_bf16_f32 %0, %1, %2" : "=v"(r) : "v"(lo), "v"(hi)); return r; }
; __device__ __forceinline__ void tconv_tile(LAS float* tile, const float* src, int ld, int k0, int n0, int mode, bf16_t* dst, int K) {
;     ...
;     for (int it = 0; it < 2; ++it) { const int idx = tid + it * 512, kk = idx >> 4, n4 = (idx & 15) * 4, nn = n0 + n4; int oc = nn; bool valid = true;
;         if (mode == 1) { if (nn < 7680) oc = nn; else if (nn < 18944) oc = nn + 48; else if (nn < INW) oc = 7680 + (nn - 18944); else valid = false; }
;         f32x4 v = (f32x4){0.f, 0.f, 0.f, 0.f}; if (valid) v = *(const f32x4*)(src + (size_t)(k0 + kk) * ld + oc);
;         tile[kk * 65 + n4 + 0] = v[0]; tile[kk * 65 + n4 + 1] = v[1]; tile[kk * 65 + n4 + 2] = v[2]; tile[kk * 65 + n4 + 3] = v[3]; }
;     __syncthreads();
;     { const int n = tid >> 3, k8 = (tid & 7) * 8; float v[8];
; #pragma unroll
;         for (int e = 0; e < 8; ++e) v[e] = tile[(k8 + e) * 65 + n];
;         u32x4 w; w.x = cvt_pk_bf16(v[0], v[1]); w.y = cvt_pk_bf16(v[2], v[3]); w.z = cvt_pk_bf16(v[4], v[5]); w.w = cvt_pk_bf16(v[6], v[7]);
;         *(u32x4*)(dst + (size_t)(n0 + n) * K + k0 + k8) = w; }
; __device__ __forceinline__ void prologue(LAS unsigned char* lds, const Ctx& P, int l) {
;     ...
;         if (q < T_BR) { const int br = q >> 9, r = q & 511, kt = r & 15, ntl = r >> 4;
;             tconv_tile(tile, P.in[23] + ((size_t)l * 4 + br) * DBR * DM, DM, kt * 64, ntl * 64, 0, (bf16_t*)(ws + WS_WBR) + (size_t)br * DM * DBR, DBR); continue; }
;         q -= T_BR;
;         if (q < T_OUT) { const int kt = q & 31, ntl = q >> 5; tconv_tile(tile, P.in[24] + (size_t)l * DM * DM, DM, kt * 64, ntl * 64, 0, (bf16_t*)(ws + WS_WOUT), DM); continue; }
.Ltc3_d106:
	v_mov_b32_e32 v42, 0
	v_mov_b32_e32 v43, 0
	v_mov_b32_e32 v44, 0
	v_mov_b32_e32 v45, 0
	v_mov_b32_e32 v46, 0
	v_mov_b32_e32 v47, 0
	v_mov_b32_e32 v48, 0
	v_mov_b32_e32 v49, 0
	v_mul_u32_u24_e32 v26, s28, v20
	v_add_lshl_u32 v26, v26, v21, 2
	s_lshl_b32 s0, s28, 7
	v_add_u32_e32 v27, s0, v26
	v_cmp_gt_i32_e32 vcc, s29, v21
	s_and_saveexec_b64 s[0:1], vcc
	global_load_dwordx4 v[42:45], v26, s[26:27] nt
	global_load_dwordx4 v[46:49], v27, s[26:27] nt
	s_mov_b64 exec, s[0:1]
	s_add_u32 s24, s24, 0xe0
	s_cmpk_ge_u32 s25, 12672
	s_cbranch_scc1 .Ltc3_exit
	s_waitcnt vmcnt(12)
	v_add_u32_e32 v28, 0, v22
	ds_write2_b32 v28, v50, v51 offset1:1
	ds_write2_b32 v28, v52, v53 offset0:2 offset1:3
	v_add_u32_e32 v28, 0x2080, v28
	ds_write2_b32 v28, v54, v55 offset1:1
	ds_write2_b32 v28, v56, v57 offset0:2 offset1:3
	s_mov_b32 s21, s25
	s_mov_b32 s0, s21
	s_cmpk_lt_u32 s0, 9600
	s_cbranch_scc0 .Ltc3_c120
	s_and_b32 s1, s0, 31
	s_lshl_b32 s1, s1, 6
	s_lshr_b32 s21, s0, 5
	s_lshl_b32 s21, s21, 17
	s_add_u32 s1, s1, s21
	s_lshl_b32 s1, s1, 1
	s_add_u32 s1, s1, 0x4001000
	s_add_u32 s30, s68, s1
	s_addc_u32 s31, s69, 0
	s_movk_i32 s20, 0x800
	s_branch .Ltc3_d119

; __device__ __forceinline__ unsigned cvt_pk_bf16(float lo, float hi) { unsigned r; asm("v_cvt_pk_bf16_f32 %0, %1, %2" : "=v"(r) : "v"(lo), "v"(hi)); return r; }
; __device__ __forceinline__ void tconv_tile(LAS float* tile, const float* src, int ld, int k0, int n0, int mode, bf16_t* dst, int K) {
;     ...
;     for (int it = 0; it < 2; ++it) { const int idx = tid + it * 512, kk = idx >> 4, n4 = (idx & 15) * 4, nn = n0 + n4; int oc = nn; bool valid = true;
;         if (mode == 1) { if (nn < 7680) oc = nn; else if (nn < 18944) oc = nn + 48; else if (nn < INW) oc = 7680 + (nn - 18944); else valid = false; }
;         f32x4 v = (f32x4){0.f, 0.f, 0.f, 0.f}; if (valid) v = *(const f32x4*)(src + (size_t)(k0 + kk) * ld + oc);
;         tile[kk * 65 + n4 + 0] = v[0]; tile[kk * 65 + n4 + 1] = v[1]; tile[kk * 65 + n4 + 2] = v[2]; tile[kk * 65 + n4 + 3] = v[3]; }
;     __syncthreads();
;     { const int n = tid >> 3, k8 = (tid & 7) * 8; float v[8];
; #pragma unroll
;         for (int e = 0; e < 8; ++e) v[e] = tile[(k8 + e) * 65 + n];
;         u32x4 w; w.x = cvt_pk_bf16(v[0], v[1]); w.y = cvt_pk_bf16(v[2], v[3]); w.z = cvt_pk_bf16(v[4], v[5]); w.w = cvt_pk_bf16(v[6], v[7]);
;         *(u32x4*)(dst + (size_t)(n0 + n) * K + k0 + k8) = w; }
; __device__ __forceinline__ void prologue(LAS unsigned char* lds, const Ctx& P, int l) {
;     ...
;         if (q < T_BR) { const int br = q >> 9, r = q & 511, kt = r & 15, ntl = r >> 4;
;             tconv_tile(tile, P.in[23] + ((size_t)l * 4 + br) * DBR * DM, DM, kt * 64, ntl * 64, 0, (bf16_t*)(ws + WS_WBR) + (size_t)br * DM * DBR, DBR); continue; }
;         q -= T_BR;
;         if (q < T_OUT) { const int kt = q & 31, ntl = q >> 5; tconv_tile(tile, P.in[24] + (size_t)l * DM * DM, DM, kt * 64, ntl * 64, 0, (bf16_t*)(ws + WS_WOUT), DM); continue; }
.Ltc3_d126:
	v_mov_b32_e32 v50, 0
	v_mov_b32_e32 v51, 0
	v_mov_b32_e32 v52, 0
	v_mov_b32_e32 v53, 0
	v_mov_b32_e32 v54, 0
	v_mov_b32_e32 v55, 0
	v_mov_b32_e32 v56, 0
	v_mov_b32_e32 v57, 0
	v_mul_u32_u24_e32 v26, s28, v20
	v_add_lshl_u32 v26, v26, v21, 2
	s_lshl_b32 s0, s28, 7
	v_add_u32_e32 v27, s0, v26
	v_cmp_gt_i32_e32 vcc, s29, v21
	s_and_saveexec_b64 s[0:1], vcc
	global_load_dwordx4 v[50:53], v26, s[26:27] nt
	global_load_dwordx4 v[54:57], v27, s[26:27] nt
	s_mov_b64 exec, s[0:1]
	s_add_u32 s24, s24, 0xe0
	s_cmpk_ge_u32 s25, 12672
	s_cbranch_scc1 .Ltc3_exit
	s_waitcnt vmcnt(13)
	v_add_u32_e32 v28, 16896, v22
	ds_write2_b32 v28, v58, v59 offset1:1
	ds_write2_b32 v28, v60, v61 offset0:2 offset1:3
	v_add_u32_e32 v28, 0x2080, v28
	ds_write2_b32 v28, v62, v63 offset1:1
	ds_write2_b32 v28, v64, v65 offset0:2 offset1:3
	s_mov_b32 s21, s25
	s_mov_b32 s0, s21
	s_cmpk_lt_u32 s0, 9600
	s_cbranch_scc0 .Ltc3_c140
	s_and_b32 s1, s0, 31
	s_lshl_b32 s1, s1, 6
	s_lshr_b32 s21, s0, 5
	s_lshl_b32 s21, s21, 17
	s_add_u32 s1, s1, s21
	s_lshl_b32 s1, s1, 1
	s_add_u32 s1, s1, 0x4001000
	s_add_u32 s30, s68, s1
	s_addc_u32 s31, s69, 0
	s_movk_i32 s20, 0x800
	s_branch .Ltc3_d139

; __device__ __forceinline__ unsigned cvt_pk_bf16(float lo, float hi) { unsigned r; asm("v_cvt_pk_bf16_f32 %0, %1, %2" : "=v"(r) : "v"(lo), "v"(hi)); return r; }
; __device__ __forceinline__ void tconv_tile(LAS float* tile, const float* src, int ld, int k0, int n0, int mode, bf16_t* dst, int K) {
;     ...
;     for (int it = 0; it < 2; ++it) { const int idx = tid + it * 512, kk = idx >> 4, n4 = (idx & 15) * 4, nn = n0 + n4; int oc = nn; bool valid = true;
;         if (mode == 1) { if (nn < 7680) oc = nn; else if (nn < 18944) oc = nn + 48; else if (nn < INW) oc = 7680 + (nn - 18944); else valid = false; }
;         f32x4 v = (f32x4){0.f, 0.f, 0.f, 0.f}; if (valid) v = *(const f32x4*)(src + (size_t)(k0 + kk) * ld + oc);
;         tile[kk * 65 + n4 + 0] = v[0]; tile[kk * 65 + n4 + 1] = v[1]; tile[kk * 65 + n4 + 2] = v[2]; tile[kk * 65 + n4 + 3] = v[3]; }
;     __syncthreads();
;     { const int n = tid >> 3, k8 = (tid & 7) * 8; float v[8];
; #pragma unroll
;         for (int e = 0; e < 8; ++e) v[e] = tile[(k8 + e) * 65 + n];
;         u32x4 w; w.x = cvt_pk_bf16(v[0], v[1]); w.y = cvt_pk_bf16(v[2], v[3]); w.z = cvt_pk_bf16(v[4], v[5]); w.w = cvt_pk_bf16(v[6], v[7]);
;         *(u32x4*)(dst + (size_t)(n0 + n) * K + k0 + k8) = w; }
; __device__ __forceinline__ void prologue(LAS unsigned char* lds, const Ctx& P, int l) {
;     ...
;         if (q < T_BR) { const int br = q >> 9, r = q & 511, kt = r & 15, ntl = r >> 4;
;             tconv_tile(tile, P.in[23] + ((size_t)l * 4 + br) * DBR * DM, DM, kt * 64, ntl * 64, 0, (bf16_t*)(ws + WS_WBR) + (size_t)br * DM * DBR, DBR); continue; }
;         q -= T_BR;
;         if (q < T_OUT) { const int kt = q & 31, ntl = q >> 5; tconv_tile(tile, P.in[24] + (size_t)l * DM * DM, DM, kt * 64, ntl * 64, 0, (bf16_t*)(ws + WS_WOUT), DM); continue; }
.Ltc3_d146:
	v_mov_b32_e32 v58, 0
	v_mov_b32_e32 v59, 0
	v_mov_b32_e32 v60, 0
	v_mov_b32_e32 v61, 0
	v_mov_b32_e32 v62, 0
	v_mov_b32_e32 v63, 0
	v_mov_b32_e32 v64, 0
	v_mov_b32_e32 v65, 0
	v_mul_u32_u24_e32 v26, s28, v20
	v_add_lshl_u32 v26, v26, v21, 2
	s_lshl_b32 s0, s28, 7
	v_add_u32_e32 v27, s0, v26
	v_cmp_gt_i32_e32 vcc, s29, v21
	s_and_saveexec_b64 s[0:1], vcc
	global_load_dwordx4 v[58:61], v26, s[26:27] nt
	global_load_dwordx4 v[62:65], v27, s[26:27] nt
	s_mov_b64 exec, s[0:1]
	s_add_u32 s24, s24, 0xe0
	s_cmpk_ge_u32 s25, 12672
	s_cbranch_scc1 .Ltc3_exit
	s_waitcnt vmcnt(14)
	v_add_u32_e32 v28, 0, v22
	ds_write2_b32 v28, v78, v79 offset1:1
	ds_write2_b32 v28, v80, v81 offset0:2 offset1:3
	v_add_u32_e32 v28, 0x2080, v28
	ds_write2_b32 v28, v82, v83 offset1:1
	ds_write2_b32 v28, v84, v85 offset0:2 offset1:3
	s_mov_b32 s21, s25
	s_mov_b32 s0, s21
	s_cmpk_lt_u32 s0, 9600
	s_cbranch_scc0 .Ltc3_c160
	s_and_b32 s1, s0, 31
	s_lshl_b32 s1, s1, 6
	s_lshr_b32 s21, s0, 5
	s_lshl_b32 s21, s21, 17
	s_add_u32 s1, s1, s21
	s_lshl_b32 s1, s1, 1
	s_add_u32 s1, s1, 0x4001000
	s_add_u32 s30, s68, s1
	s_addc_u32 s31, s69, 0
	s_movk_i32 s20, 0x800
	s_branch .Ltc3_d159

; __device__ __forceinline__ unsigned cvt_pk_bf16(float lo, float hi) { unsigned r; asm("v_cvt_pk_bf16_f32 %0, %1, %2" : "=v"(r) : "v"(lo), "v"(hi)); return r; }
; __device__ __forceinline__ void tconv_tile(LAS float* tile, const float* src, int ld, int k0, int n0, int mode, bf16_t* dst, int K) {
;     ...
;     for (int it = 0; it < 2; ++it) { const int idx = tid + it * 512, kk = idx >> 4, n4 = (idx & 15) * 4, nn = n0 + n4; int oc = nn; bool valid = true;
;         if (mode == 1) { if (nn < 7680) oc = nn; else if (nn < 18944) oc = nn + 48; else if (nn < INW) oc = 7680 + (nn - 18944); else valid = false; }
;         f32x4 v = (f32x4){0.f, 0.f, 0.f, 0.f}; if (valid) v = *(const f32x4*)(src + (size_t)(k0 + kk) * ld + oc);
;         tile[kk * 65 + n4 + 0] = v[0]; tile[kk * 65 + n4 + 1] = v[1]; tile[kk * 65 + n4 + 2] = v[2]; tile[kk * 65 + n4 + 3] = v[3]; }
;     __syncthreads();
;     { const int n = tid >> 3, k8 = (tid & 7) * 8; float v[8];
; #pragma unroll
;         for (int e = 0; e < 8; ++e) v[e] = tile[(k8 + e) * 65 + n];
;         u32x4 w; w.x = cvt_pk_bf16(v[0], v[1]); w.y = cvt_pk_bf16(v[2], v[3]); w.z = cvt_pk_bf16(v[4], v[5]); w.w = cvt_pk_bf16(v[6], v[7]);
;         *(u32x4*)(dst + (size_t)(n0 + n) * K + k0 + k8) = w; }
; __device__ __forceinline__ void prologue(LAS unsigned char* lds, const Ctx& P, int l) {
;     ...
;         if (q < T_BR) { const int br = q >> 9, r = q & 511, kt = r & 15, ntl = r >> 4;
;             tconv_tile(tile, P.in[23] + ((size_t)l * 4 + br) * DBR * DM, DM, kt * 64, ntl * 64, 0, (bf16_t*)(ws + WS_WBR) + (size_t)br * DM * DBR, DBR); continue; }
;         q -= T_BR;
;         if (q < T_OUT) { const int kt = q & 31, ntl = q >> 5; tconv_tile(tile, P.in[24] + (size_t)l * DM * DM, DM, kt * 64, ntl * 64, 0, (bf16_t*)(ws + WS_WOUT), DM); continue; }
.Ltc3_d166:
	v_mov_b32_e32 v78, 0
	v_mov_b32_e32 v79, 0
	v_mov_b32_e32 v80, 0
	v_mov_b32_e32 v81, 0
	v_mov_b32_e32 v82, 0
	v_mov_b32_e32 v83, 0
	v_mov_b32_e32 v84, 0
	v_mov_b32_e32 v85, 0
	v_mul_u32_u24_e32 v26, s28, v20
	v_add_lshl_u32 v26, v26, v21, 2
	s_lshl_b32 s0, s28, 7
	v_add_u32_e32 v27, s0, v26
	v_cmp_gt_i32_e32 vcc, s29, v21
	s_and_saveexec_b64 s[0:1], vcc
	global_load_dwordx4 v[78:81], v26, s[26:27] nt
	global_load_dwordx4 v[82:85], v27, s[26:27] nt
	s_mov_b64 exec, s[0:1]
	s_add_u32 s24, s24, 0xe0
	s_cmpk_ge_u32 s25, 12672
	s_cbranch_scc1 .Ltc3_exit
	s_waitcnt vmcnt(15)
	v_add_u32_e32 v28, 16896, v22
	ds_write2_b32 v28, v86, v87 offset1:1
	ds_write2_b32 v28, v88, v89 offset0:2 offset1:3
	v_add_u32_e32 v28, 0x2080, v28
	ds_write2_b32 v28, v90, v91 offset1:1
	ds_write2_b32 v28, v92, v93 offset0:2 offset1:3
	s_mov_b32 s21, s25
	s_mov_b32 s0, s21
	s_cmpk_lt_u32 s0, 9600
	s_cbranch_scc0 .Ltc3_c180
	s_and_b32 s1, s0, 31
	s_lshl_b32 s1, s1, 6
	s_lshr_b32 s21, s0, 5
	s_lshl_b32 s21, s21, 17
	s_add_u32 s1, s1, s21
	s_lshl_b32 s1, s1, 1
	s_add_u32 s1, s1, 0x4001000
	s_add_u32 s30, s68, s1
	s_addc_u32 s31, s69, 0
	s_movk_i32 s20, 0x800
	s_branch .Ltc3_d179

; __device__ __forceinline__ unsigned cvt_pk_bf16(float lo, float hi) { unsigned r; asm("v_cvt_pk_bf16_f32 %0, %1, %2" : "=v"(r) : "v"(lo), "v"(hi)); return r; }
; __device__ __forceinline__ void tconv_tile(LAS float* tile, const float* src, int ld, int k0, int n0, int mode, bf16_t* dst, int K) {
;     ...
;     for (int it = 0; it < 2; ++it) { const int idx = tid + it * 512, kk = idx >> 4, n4 = (idx & 15) * 4, nn = n0 + n4; int oc = nn; bool valid = true;
;         if (mode == 1) { if (nn < 7680) oc = nn; else if (nn < 18944) oc = nn + 48; else if (nn < INW) oc = 7680 + (nn - 18944); else valid = false; }
;         f32x4 v = (f32x4){0.f, 0.f, 0.f, 0.f}; if (valid) v = *(const f32x4*)(src + (size_t)(k0 + kk) * ld + oc);
;         tile[kk * 65 + n4 + 0] = v[0]; tile[kk * 65 + n4 + 1] = v[1]; tile[kk * 65 + n4 + 2] = v[2]; tile[kk * 65 + n4 + 3] = v[3]; }
;     __syncthreads();
;     { const int n = tid >> 3, k8 = (tid & 7) * 8; float v[8];
; #pragma unroll
;         for (int e = 0; e < 8; ++e) v[e] = tile[(k8 + e) * 65 + n];
;         u32x4 w; w.x = cvt_pk_bf16(v[0], v[1]); w.y = cvt_pk_bf16(v[2], v[3]); w.z = cvt_pk_bf16(v[4], v[5]); w.w = cvt_pk_bf16(v[6], v[7]);
;         *(u32x4*)(dst + (size_t)(n0 + n) * K + k0 + k8) = w; }
; __device__ __forceinline__ void prologue(LAS unsigned char* lds, const Ctx& P, int l) {
;     ...
;         if (q < T_BR) { const int br = q >> 9, r = q & 511, kt = r & 15, ntl = r >> 4;
;             tconv_tile(tile, P.in[23] + ((size_t)l * 4 + br) * DBR * DM, DM, kt * 64, ntl * 64, 0, (bf16_t*)(ws + WS_WBR) + (size_t)br * DM * DBR, DBR); continue; }
;         q -= T_BR;
;         if (q < T_OUT) { const int kt = q & 31, ntl = q >> 5; tconv_tile(tile, P.in[24] + (size_t)l * DM * DM, DM, kt * 64, ntl * 64, 0, (bf16_t*)(ws + WS_WOUT), DM); continue; }
.Ltc3_loop:
	s_cmpk_ge_u32 s25, 12672
	s_cbranch_scc1 .Ltc3_exit
	s_waitcnt vmcnt(15)
	v_add_u32_e32 v28, 0, v22
	ds_write2_b32 v28, v34, v35 offset1:1
	ds_write2_b32 v28, v36, v37 offset0:2 offset1:3
	v_add_u32_e32 v28, 0x2080, v28
	ds_write2_b32 v28, v38, v39 offset1:1
	ds_write2_b32 v28, v40, v41 offset0:2 offset1:3
	s_mov_b32 s21, s25
	s_mov_b32 s0, s21
	s_cmpk_lt_u32 s0, 9600
	s_cbranch_scc0 .Ltc3_c200
	s_and_b32 s1, s0, 31
	s_lshl_b32 s1, s1, 6
	s_lshr_b32 s21, s0, 5
	s_lshl_b32 s21, s21, 17
	s_add_u32 s1, s1, s21
	s_lshl_b32 s1, s1, 1
	s_add_u32 s1, s1, 0x4001000
	s_add_u32 s30, s68, s1
	s_addc_u32 s31, s69, 0
	s_movk_i32 s20, 0x800
	s_branch .Ltc3_d199

; __device__ __forceinline__ unsigned cvt_pk_bf16(float lo, float hi) { unsigned r; asm("v_cvt_pk_bf16_f32 %0, %1, %2" : "=v"(r) : "v"(lo), "v"(hi)); return r; }
; __device__ __forceinline__ void tconv_tile(LAS float* tile, const float* src, int ld, int k0, int n0, int mode, bf16_t* dst, int K) {
;     ...
;     for (int it = 0; it < 2; ++it) { const int idx = tid + it * 512, kk = idx >> 4, n4 = (idx & 15) * 4, nn = n0 + n4; int oc = nn; bool valid = true;
;         if (mode == 1) { if (nn < 7680) oc = nn; else if (nn < 18944) oc = nn + 48; else if (nn < INW) oc = 7680 + (nn - 18944); else valid = false; }
;         f32x4 v = (f32x4){0.f, 0.f, 0.f, 0.f}; if (valid) v = *(const f32x4*)(src + (size_t)(k0 + kk) * ld + oc);
;         tile[kk * 65 + n4 + 0] = v[0]; tile[kk * 65 + n4 + 1] = v[1]; tile[kk * 65 + n4 + 2] = v[2]; tile[kk * 65 + n4 + 3] = v[3]; }
;     __syncthreads();
;     { const int n = tid >> 3, k8 = (tid & 7) * 8; float v[8];
; #pragma unroll
;         for (int e = 0; e < 8; ++e) v[e] = tile[(k8 + e) * 65 + n];
;         u32x4 w; w.x = cvt_pk_bf16(v[0], v[1]); w.y = cvt_pk_bf16(v[2], v[3]); w.z = cvt_pk_bf16(v[4], v[5]); w.w = cvt_pk_bf16(v[6], v[7]);
;         *(u32x4*)(dst + (size_t)(n0 + n) * K + k0 + k8) = w; }
; __device__ __forceinline__ void prologue(LAS unsigned char* lds, const Ctx& P, int l) {
;     ...
;         if (q < T_BR) { const int br = q >> 9, r = q & 511, kt = r & 15, ntl = r >> 4;
;             tconv_tile(tile, P.in[23] + ((size_t)l * 4 + br) * DBR * DM, DM, kt * 64, ntl * 64, 0, (bf16_t*)(ws + WS_WBR) + (size_t)br * DM * DBR, DBR); continue; }
;         q -= T_BR;
;         if (q < T_OUT) { const int kt = q & 31, ntl = q >> 5; tconv_tile(tile, P.in[24] + (size_t)l * DM * DM, DM, kt * 64, ntl * 64, 0, (bf16_t*)(ws + WS_WOUT), DM); continue; }
.Ltc3_d206:
	v_mov_b32_e32 v34, 0
	v_mov_b32_e32 v35, 0
	v_mov_b32_e32 v36, 0
	v_mov_b32_e32 v37, 0
	v_mov_b32_e32 v38, 0
	v_mov_b32_e32 v39, 0
	v_mov_b32_e32 v40, 0
	v_mov_b32_e32 v41, 0
	v_mul_u32_u24_e32 v26, s28, v20
	v_add_lshl_u32 v26, v26, v21, 2
	s_lshl_b32 s0, s28, 7
	v_add_u32_e32 v27, s0, v26
	v_cmp_gt_i32_e32 vcc, s29, v21
	s_and_saveexec_b64 s[0:1], vcc
	global_load_dwordx4 v[34:37], v26, s[26:27] nt
	global_load_dwordx4 v[38:41], v27, s[26:27] nt
	s_mov_b64 exec, s[0:1]
	s_add_u32 s24, s24, 0xe0
	s_cmpk_ge_u32 s25, 12672
	s_cbranch_scc1 .Ltc3_exit
	s_waitcnt vmcnt(15)
	v_add_u32_e32 v28, 16896, v22
	ds_write2_b32 v28, v42, v43 offset1:1
	ds_write2_b32 v28, v44, v45 offset0:2 offset1:3
	v_add_u32_e32 v28, 0x2080, v28
	ds_write2_b32 v28, v46, v47 offset1:1
	ds_write2_b32 v28, v48, v49 offset0:2 offset1:3
	s_mov_b32 s21, s25
	s_mov_b32 s0, s21
	s_cmpk_lt_u32 s0, 9600
	s_cbranch_scc0 .Ltc3_c220
	s_and_b32 s1, s0, 31
	s_lshl_b32 s1, s1, 6
	s_lshr_b32 s21, s0, 5
	s_lshl_b32 s21, s21, 17
	s_add_u32 s1, s1, s21
	s_lshl_b32 s1, s1, 1
	s_add_u32 s1, s1, 0x4001000
	s_add_u32 s30, s68, s1
	s_addc_u32 s31, s69, 0
	s_movk_i32 s20, 0x800
	s_branch .Ltc3_d219

; __device__ __forceinline__ unsigned cvt_pk_bf16(float lo, float hi) { unsigned r; asm("v_cvt_pk_bf16_f32 %0, %1, %2" : "=v"(r) : "v"(lo), "v"(hi)); return r; }
; __device__ __forceinline__ void tconv_tile(LAS float* tile, const float* src, int ld, int k0, int n0, int mode, bf16_t* dst, int K) {
;     ...
;     for (int it = 0; it < 2; ++it) { const int idx = tid + it * 512, kk = idx >> 4, n4 = (idx & 15) * 4, nn = n0 + n4; int oc = nn; bool valid = true;
;         if (mode == 1) { if (nn < 7680) oc = nn; else if (nn < 18944) oc = nn + 48; else if (nn < INW) oc = 7680 + (nn - 18944); else valid = false; }
;         f32x4 v = (f32x4){0.f, 0.f, 0.f, 0.f}; if (valid) v = *(const f32x4*)(src + (size_t)(k0 + kk) * ld + oc);
;         tile[kk * 65 + n4 + 0] = v[0]; tile[kk * 65 + n4 + 1] = v[1]; tile[kk * 65 + n4 + 2] = v[2]; tile[kk * 65 + n4 + 3] = v[3]; }
;     __syncthreads();
;     { const int n = tid >> 3, k8 = (tid & 7) * 8; float v[8];
; #pragma unroll
;         for (int e = 0; e < 8; ++e) v[e] = tile[(k8 + e) * 65 + n];
;         u32x4 w; w.x = cvt_pk_bf16(v[0], v[1]); w.y = cvt_pk_bf16(v[2], v[3]); w.z = cvt_pk_bf16(v[4], v[5]); w.w = cvt_pk_bf16(v[6], v[7]);
;         *(u32x4*)(dst + (size_t)(n0 + n) * K + k0 + k8) = w; }
; __device__ __forceinline__ void prologue(LAS unsigned char* lds, const Ctx& P, int l) {
;     ...
;         if (q < T_BR) { const int br = q >> 9, r = q & 511, kt = r & 15, ntl = r >> 4;
;             tconv_tile(tile, P.in[23] + ((size_t)l * 4 + br) * DBR * DM, DM, kt * 64, ntl * 64, 0, (bf16_t*)(ws + WS_WBR) + (size_t)br * DM * DBR, DBR); continue; }
;         q -= T_BR;
;         if (q < T_OUT) { const int kt = q & 31, ntl = q >> 5; tconv_tile(tile, P.in[24] + (size_t)l * DM * DM, DM, kt * 64, ntl * 64, 0, (bf16_t*)(ws + WS_WOUT), DM); continue; }
.Ltc3_d226:
	v_mov_b32_e32 v42, 0
	v_mov_b32_e32 v43, 0
	v_mov_b32_e32 v44, 0
	v_mov_b32_e32 v45, 0
	v_mov_b32_e32 v46, 0
	v_mov_b32_e32 v47, 0
	v_mov_b32_e32 v48, 0
	v_mov_b32_e32 v49, 0
	v_mul_u32_u24_e32 v26, s28, v20
	v_add_lshl_u32 v26, v26, v21, 2
	s_lshl_b32 s0, s28, 7
	v_add_u32_e32 v27, s0, v26
	v_cmp_gt_i32_e32 vcc, s29, v21
	s_and_saveexec_b64 s[0:1], vcc
	global_load_dwordx4 v[42:45], v26, s[26:27] nt
	global_load_dwordx4 v[46:49], v27, s[26:27] nt
	s_mov_b64 exec, s[0:1]
	s_add_u32 s24, s24, 0xe0
	s_cmpk_ge_u32 s25, 12672
	s_cbranch_scc1 .Ltc3_exit
	s_waitcnt vmcnt(15)
	v_add_u32_e32 v28, 0, v22
	ds_write2_b32 v28, v50, v51 offset1:1
	ds_write2_b32 v28, v52, v53 offset0:2 offset1:3
	v_add_u32_e32 v28, 0x2080, v28
	ds_write2_b32 v28, v54, v55 offset1:1
	ds_write2_b32 v28, v56, v57 offset0:2 offset1:3
	s_mov_b32 s21, s25
	s_mov_b32 s0, s21
	s_cmpk_lt_u32 s0, 9600
	s_cbranch_scc0 .Ltc3_c240
	s_and_b32 s1, s0, 31
	s_lshl_b32 s1, s1, 6
	s_lshr_b32 s21, s0, 5
	s_lshl_b32 s21, s21, 17
	s_add_u32 s1, s1, s21
	s_lshl_b32 s1, s1, 1
	s_add_u32 s1, s1, 0x4001000
	s_add_u32 s30, s68, s1
	s_addc_u32 s31, s69, 0
	s_movk_i32 s20, 0x800
	s_branch .Ltc3_d239

; __device__ __forceinline__ unsigned cvt_pk_bf16(float lo, float hi) { unsigned r; asm("v_cvt_pk_bf16_f32 %0, %1, %2" : "=v"(r) : "v"(lo), "v"(hi)); return r; }
; __device__ __forceinline__ void tconv_tile(LAS float* tile, const float* src, int ld, int k0, int n0, int mode, bf16_t* dst, int K) {
;     ...
;     for (int it = 0; it < 2; ++it) { const int idx = tid + it * 512, kk = idx >> 4, n4 = (idx & 15) * 4, nn = n0 + n4; int oc = nn; bool valid = true;
;         if (mode == 1) { if (nn < 7680) oc = nn; else if (nn < 18944) oc = nn + 48; else if (nn < INW) oc = 7680 + (nn - 18944); else valid = false; }
;         f32x4 v = (f32x4){0.f, 0.f, 0.f, 0.f}; if (valid) v = *(const f32x4*)(src + (size_t)(k0 + kk) * ld + oc);
;         tile[kk * 65 + n4 + 0] = v[0]; tile[kk * 65 + n4 + 1] = v[1]; tile[kk * 65 + n4 + 2] = v[2]; tile[kk * 65 + n4 + 3] = v[3]; }
;     __syncthreads();
;     { const int n = tid >> 3, k8 = (tid & 7) * 8; float v[8];
; #pragma unroll
;         for (int e = 0; e < 8; ++e) v[e] = tile[(k8 + e) * 65 + n];
;         u32x4 w; w.x = cvt_pk_bf16(v[0], v[1]); w.y = cvt_pk_bf16(v[2], v[3]); w.z = cvt_pk_bf16(v[4], v[5]); w.w = cvt_pk_bf16(v[6], v[7]);
;         *(u32x4*)(dst + (size_t)(n0 + n) * K + k0 + k8) = w; }
; __device__ __forceinline__ void prologue(LAS unsigned char* lds, const Ctx& P, int l) {
;     ...
;         if (q < T_BR) { const int br = q >> 9, r = q & 511, kt = r & 15, ntl = r >> 4;
;             tconv_tile(tile, P.in[23] + ((size_t)l * 4 + br) * DBR * DM, DM, kt * 64, ntl * 64, 0, (bf16_t*)(ws + WS_WBR) + (size_t)br * DM * DBR, DBR); continue; }
;         q -= T_BR;
;         if (q < T_OUT) { const int kt = q & 31, ntl = q >> 5; tconv_tile(tile, P.in[24] + (size_t)l * DM * DM, DM, kt * 64, ntl * 64, 0, (bf16_t*)(ws + WS_WOUT), DM); continue; }
.Ltc3_d246:
	v_mov_b32_e32 v50, 0
	v_mov_b32_e32 v51, 0
	v_mov_b32_e32 v52, 0
	v_mov_b32_e32 v53, 0
	v_mov_b32_e32 v54, 0
	v_mov_b32_e32 v55, 0
	v_mov_b32_e32 v56, 0
	v_mov_b32_e32 v57, 0
	v_mul_u32_u24_e32 v26, s28, v20
	v_add_lshl_u32 v26, v26, v21, 2
	s_lshl_b32 s0, s28, 7
	v_add_u32_e32 v27, s0, v26
	v_cmp_gt_i32_e32 vcc, s29, v21
	s_and_saveexec_b64 s[0:1], vcc
	global_load_dwordx4 v[50:53], v26, s[26:27] nt
	global_load_dwordx4 v[54:57], v27, s[26:27] nt
	s_mov_b64 exec, s[0:1]
	s_add_u32 s24, s24, 0xe0
	s_cmpk_ge_u32 s25, 12672
	s_cbranch_scc1 .Ltc3_exit
	s_waitcnt vmcnt(15)
	v_add_u32_e32 v28, 16896, v22
	ds_write2_b32 v28, v58, v59 offset1:1
	ds_write2_b32 v28, v60, v61 offset0:2 offset1:3
	v_add_u32_e32 v28, 0x2080, v28
	ds_write2_b32 v28, v62, v63 offset1:1
	ds_write2_b32 v28, v64, v65 offset0:2 offset1:3
	s_mov_b32 s21, s25
	s_mov_b32 s0, s21
	s_cmpk_lt_u32 s0, 9600
	s_cbranch_scc0 .Ltc3_c260
	s_and_b32 s1, s0, 31
	s_lshl_b32 s1, s1, 6
	s_lshr_b32 s21, s0, 5
	s_lshl_b32 s21, s21, 17
	s_add_u32 s1, s1, s21
	s_lshl_b32 s1, s1, 1
	s_add_u32 s1, s1, 0x4001000
	s_add_u32 s30, s68, s1
	s_addc_u32 s31, s69, 0
	s_movk_i32 s20, 0x800
	s_branch .Ltc3_d259

; __device__ __forceinline__ unsigned cvt_pk_bf16(float lo, float hi) { unsigned r; asm("v_cvt_pk_bf16_f32 %0, %1, %2" : "=v"(r) : "v"(lo), "v"(hi)); return r; }
; __device__ __forceinline__ void tconv_tile(LAS float* tile, const float* src, int ld, int k0, int n0, int mode, bf16_t* dst, int K) {
;     ...
;     for (int it = 0; it < 2; ++it) { const int idx = tid + it * 512, kk = idx >> 4, n4 = (idx & 15) * 4, nn = n0 + n4; int oc = nn; bool valid = true;
;         if (mode == 1) { if (nn < 7680) oc = nn; else if (nn < 18944) oc = nn + 48; else if (nn < INW) oc = 7680 + (nn - 18944); else valid = false; }
;         f32x4 v = (f32x4){0.f, 0.f, 0.f, 0.f}; if (valid) v = *(const f32x4*)(src + (size_t)(k0 + kk) * ld + oc);
;         tile[kk * 65 + n4 + 0] = v[0]; tile[kk * 65 + n4 + 1] = v[1]; tile[kk * 65 + n4 + 2] = v[2]; tile[kk * 65 + n4 + 3] = v[3]; }
;     __syncthreads();
;     { const int n = tid >> 3, k8 = (tid & 7) * 8; float v[8];
; #pragma unroll
;         for (int e = 0; e < 8; ++e) v[e] = tile[(k8 + e) * 65 + n];
;         u32x4 w; w.x = cvt_pk_bf16(v[0], v[1]); w.y = cvt_pk_bf16(v[2], v[3]); w.z = cvt_pk_bf16(v[4], v[5]); w.w = cvt_pk_bf16(v[6], v[7]);
;         *(u32x4*)(dst + (size_t)(n0 + n) * K + k0 + k8) = w; }
; __device__ __forceinline__ void prologue(LAS unsigned char* lds, const Ctx& P, int l) {
;     ...
;         if (q < T_BR) { const int br = q >> 9, r = q & 511, kt = r & 15, ntl = r >> 4;
;             tconv_tile(tile, P.in[23] + ((size_t)l * 4 + br) * DBR * DM, DM, kt * 64, ntl * 64, 0, (bf16_t*)(ws + WS_WBR) + (size_t)br * DM * DBR, DBR); continue; }
;         q -= T_BR;
;         if (q < T_OUT) { const int kt = q & 31, ntl = q >> 5; tconv_tile(tile, P.in[24] + (size_t)l * DM * DM, DM, kt * 64, ntl * 64, 0, (bf16_t*)(ws + WS_WOUT), DM); continue; }
.Ltc3_d266:
	v_mov_b32_e32 v58, 0
	v_mov_b32_e32 v59, 0
	v_mov_b32_e32 v60, 0
	v_mov_b32_e32 v61, 0
	v_mov_b32_e32 v62, 0
	v_mov_b32_e32 v63, 0
	v_mov_b32_e32 v64, 0
	v_mov_b32_e32 v65, 0
	v_mul_u32_u24_e32 v26, s28, v20
	v_add_lshl_u32 v26, v26, v21, 2
	s_lshl_b32 s0, s28, 7
	v_add_u32_e32 v27, s0, v26
	v_cmp_gt_i32_e32 vcc, s29, v21
	s_and_saveexec_b64 s[0:1], vcc
	global_load_dwordx4 v[58:61], v26, s[26:27] nt
	global_load_dwordx4 v[62:65], v27, s[26:27] nt
	s_mov_b64 exec, s[0:1]
	s_add_u32 s24, s24, 0xe0
	s_cmpk_ge_u32 s25, 12672
	s_cbranch_scc1 .Ltc3_exit
	s_waitcnt vmcnt(15)
	v_add_u32_e32 v28, 0, v22
	ds_write2_b32 v28, v78, v79 offset1:1
	ds_write2_b32 v28, v80, v81 offset0:2 offset1:3
	v_add_u32_e32 v28, 0x2080, v28
	ds_write2_b32 v28, v82, v83 offset1:1
	ds_write2_b32 v28, v84, v85 offset0:2 offset1:3
	s_mov_b32 s21, s25
	s_mov_b32 s0, s21
	s_cmpk_lt_u32 s0, 9600
	s_cbranch_scc0 .Ltc3_c280
	s_and_b32 s1, s0, 31
	s_lshl_b32 s1, s1, 6
	s_lshr_b32 s21, s0, 5
	s_lshl_b32 s21, s21, 17
	s_add_u32 s1, s1, s21
	s_lshl_b32 s1, s1, 1
	s_add_u32 s1, s1, 0x4001000
	s_add_u32 s30, s68, s1
	s_addc_u32 s31, s69, 0
	s_movk_i32 s20, 0x800
	s_branch .Ltc3_d279

; __device__ __forceinline__ void tconv_tile(LAS float* tile, const float* src, int ld, int k0, int n0, int mode, bf16_t* dst, int K) {
;     ...
;     for (int it = 0; it < 2; ++it) { const int idx = tid + it * 512, kk = idx >> 4, n4 = (idx & 15) * 4, nn = n0 + n4; int oc = nn; bool valid = true;
;         if (mode == 1) { if (nn < 7680) oc = nn; else if (nn < 18944) oc = nn + 48; else if (nn < INW) oc = 7680 + (nn - 18944); else valid = false; }
;         f32x4 v = (f32x4){0.f, 0.f, 0.f, 0.f}; if (valid) v = *(const f32x4*)(src + (size_t)(k0 + kk) * ld + oc);
; __device__ __forceinline__ void prologue(LAS unsigned char* lds, const Ctx& P, int l) {
;     ...
;     for (int t = blockIdx.x; t < T_ALL; t += G) {
;         int q = t;
;         if (q < T_IN) { const int kt = q & 31, ntl = q >> 5; tconv_tile(tile, P.in[3] + (size_t)l * DM * INW, INW, kt * 64, ntl * 64, 1, (bf16_t*)(ws + WS_WIN), DM); continue; }
.Ltc1_d1:
	v_mov_b32_e32 v34, 0
	v_mov_b32_e32 v35, 0
	v_mov_b32_e32 v36, 0
	v_mov_b32_e32 v37, 0
	v_mov_b32_e32 v38, 0
	v_mov_b32_e32 v39, 0
	v_mov_b32_e32 v40, 0
	v_mov_b32_e32 v41, 0
	v_mul_u32_u24_e32 v26, s28, v20
	v_add_lshl_u32 v26, v26, v21, 2
	s_lshl_b32 s0, s28, 7
	v_add_u32_e32 v27, s0, v26
	v_cmp_gt_i32_e32 vcc, s29, v21
	s_and_saveexec_b64 s[0:1], vcc
	global_load_dwordx4 v[34:37], v26, s[26:27]
	global_load_dwordx4 v[38:41], v27, s[26:27]
	s_mov_b64 exec, s[0:1]
	s_add_u32 s24, s24, s34
	s_sub_u32 s1, s24, 9600
	s_cmpk_lt_u32 s1, 3072
	s_cselect_b32 s1, 3072, 0
	s_add_u32 s24, s24, s1
	s_min_u32 s0, s24, 14015
	s_mov_b32 s21, s0
	s_mov_b32 s0, s21
	s_cmpk_lt_u32 s0, 9600
	s_cbranch_scc0 .Ltc1_c15
	s_and_b32 s1, s0, 31
	s_lshl_b32 s1, s1, 6
	s_lshr_b32 s21, s0, 5
	s_lshl_b32 s21, s21, 6
	s_movk_i32 s29, 64
	s_cmpk_lt_u32 s21, 7680
	s_cbranch_scc1 .Ltc1_n17
	s_cmpk_lt_u32 s21, 18944
	s_cbranch_scc0 .Ltc1_t16
	s_add_u32 s21, s21, 48
	s_branch .Ltc1_n17

; __device__ __forceinline__ void tconv_tile(LAS float* tile, const float* src, int ld, int k0, int n0, int mode, bf16_t* dst, int K) {
;     ...
;     for (int it = 0; it < 2; ++it) { const int idx = tid + it * 512, kk = idx >> 4, n4 = (idx & 15) * 4, nn = n0 + n4; int oc = nn; bool valid = true;
;         if (mode == 1) { if (nn < 7680) oc = nn; else if (nn < 18944) oc = nn + 48; else if (nn < INW) oc = 7680 + (nn - 18944); else valid = false; }
;         f32x4 v = (f32x4){0.f, 0.f, 0.f, 0.f}; if (valid) v = *(const f32x4*)(src + (size_t)(k0 + kk) * ld + oc);
; __device__ __forceinline__ void prologue(LAS unsigned char* lds, const Ctx& P, int l) {
;     ...
;     for (int t = blockIdx.x; t < T_ALL; t += G) {
;         int q = t;
;         if (q < T_IN) { const int kt = q & 31, ntl = q >> 5; tconv_tile(tile, P.in[3] + (size_t)l * DM * INW, INW, kt * 64, ntl * 64, 1, (bf16_t*)(ws + WS_WIN), DM); continue; }
.Ltc1_d14:
	v_mov_b32_e32 v42, 0
	v_mov_b32_e32 v43, 0
	v_mov_b32_e32 v44, 0
	v_mov_b32_e32 v45, 0
	v_mov_b32_e32 v46, 0
	v_mov_b32_e32 v47, 0
	v_mov_b32_e32 v48, 0
	v_mov_b32_e32 v49, 0
	v_mul_u32_u24_e32 v26, s28, v20
	v_add_lshl_u32 v26, v26, v21, 2
	s_lshl_b32 s0, s28, 7
	v_add_u32_e32 v27, s0, v26
	v_cmp_gt_i32_e32 vcc, s29, v21
	s_and_saveexec_b64 s[0:1], vcc
	global_load_dwordx4 v[42:45], v26, s[26:27]
	global_load_dwordx4 v[46:49], v27, s[26:27]
	s_mov_b64 exec, s[0:1]
	s_add_u32 s24, s24, s34
	s_sub_u32 s1, s24, 9600
	s_cmpk_lt_u32 s1, 3072
	s_cselect_b32 s1, 3072, 0
	s_add_u32 s24, s24, s1
	s_min_u32 s0, s24, 14015
	s_mov_b32 s21, s0
	s_mov_b32 s0, s21
	s_cmpk_lt_u32 s0, 9600
	s_cbranch_scc0 .Ltc1_c28
	s_and_b32 s1, s0, 31
	s_lshl_b32 s1, s1, 6
	s_lshr_b32 s21, s0, 5
	s_lshl_b32 s21, s21, 6
	s_movk_i32 s29, 64
	s_cmpk_lt_u32 s21, 7680
	s_cbranch_scc1 .Ltc1_n30
	s_cmpk_lt_u32 s21, 18944
	s_cbranch_scc0 .Ltc1_t29
	s_add_u32 s21, s21, 48
	s_branch .Ltc1_n30

; __device__ __forceinline__ void tconv_tile(LAS float* tile, const float* src, int ld, int k0, int n0, int mode, bf16_t* dst, int K) {
;     ...
;     for (int it = 0; it < 2; ++it) { const int idx = tid + it * 512, kk = idx >> 4, n4 = (idx & 15) * 4, nn = n0 + n4; int oc = nn; bool valid = true;
;         if (mode == 1) { if (nn < 7680) oc = nn; else if (nn < 18944) oc = nn + 48; else if (nn < INW) oc = 7680 + (nn - 18944); else valid = false; }
;         f32x4 v = (f32x4){0.f, 0.f, 0.f, 0.f}; if (valid) v = *(const f32x4*)(src + (size_t)(k0 + kk) * ld + oc);
; __device__ __forceinline__ void prologue(LAS unsigned char* lds, const Ctx& P, int l) {
;     ...
;     for (int t = blockIdx.x; t < T_ALL; t += G) {
;         int q = t;
;         if (q < T_IN) { const int kt = q & 31, ntl = q >> 5; tconv_tile(tile, P.in[3] + (size_t)l * DM * INW, INW, kt * 64, ntl * 64, 1, (bf16_t*)(ws + WS_WIN), DM); continue; }
.Ltc1_d27:
	v_mov_b32_e32 v50, 0
	v_mov_b32_e32 v51, 0
	v_mov_b32_e32 v52, 0
	v_mov_b32_e32 v53, 0
	v_mov_b32_e32 v54, 0
	v_mov_b32_e32 v55, 0
	v_mov_b32_e32 v56, 0
	v_mov_b32_e32 v57, 0
	v_mul_u32_u24_e32 v26, s28, v20
	v_add_lshl_u32 v26, v26, v21, 2
	s_lshl_b32 s0, s28, 7
	v_add_u32_e32 v27, s0, v26
	v_cmp_gt_i32_e32 vcc, s29, v21
	s_and_saveexec_b64 s[0:1], vcc
	global_load_dwordx4 v[50:53], v26, s[26:27]
	global_load_dwordx4 v[54:57], v27, s[26:27]
	s_mov_b64 exec, s[0:1]
	s_add_u32 s24, s24, s34
	s_sub_u32 s1, s24, 9600
	s_cmpk_lt_u32 s1, 3072
	s_cselect_b32 s1, 3072, 0
	s_add_u32 s24, s24, s1
	s_min_u32 s0, s24, 14015
	s_mov_b32 s21, s0
	s_mov_b32 s0, s21
	s_cmpk_lt_u32 s0, 9600
	s_cbranch_scc0 .Ltc1_c41
	s_and_b32 s1, s0, 31
	s_lshl_b32 s1, s1, 6
	s_lshr_b32 s21, s0, 5
	s_lshl_b32 s21, s21, 6
	s_movk_i32 s29, 64
	s_cmpk_lt_u32 s21, 7680
	s_cbranch_scc1 .Ltc1_n43
	s_cmpk_lt_u32 s21, 18944
	s_cbranch_scc0 .Ltc1_t42
	s_add_u32 s21, s21, 48
	s_branch .Ltc1_n43

; __device__ __forceinline__ void tconv_tile(LAS float* tile, const float* src, int ld, int k0, int n0, int mode, bf16_t* dst, int K) {
;     ...
;     for (int it = 0; it < 2; ++it) { const int idx = tid + it * 512, kk = idx >> 4, n4 = (idx & 15) * 4, nn = n0 + n4; int oc = nn; bool valid = true;
;         if (mode == 1) { if (nn < 7680) oc = nn; else if (nn < 18944) oc = nn + 48; else if (nn < INW) oc = 7680 + (nn - 18944); else valid = false; }
;         f32x4 v = (f32x4){0.f, 0.f, 0.f, 0.f}; if (valid) v = *(const f32x4*)(src + (size_t)(k0 + kk) * ld + oc);
; __device__ __forceinline__ void prologue(LAS unsigned char* lds, const Ctx& P, int l) {
;     ...
;     for (int t = blockIdx.x; t < T_ALL; t += G) {
;         int q = t;
;         if (q < T_IN) { const int kt = q & 31, ntl = q >> 5; tconv_tile(tile, P.in[3] + (size_t)l * DM * INW, INW, kt * 64, ntl * 64, 1, (bf16_t*)(ws + WS_WIN), DM); continue; }
.Ltc1_d40:
	v_mov_b32_e32 v58, 0
	v_mov_b32_e32 v59, 0
	v_mov_b32_e32 v60, 0
	v_mov_b32_e32 v61, 0
	v_mov_b32_e32 v62, 0
	v_mov_b32_e32 v63, 0
	v_mov_b32_e32 v64, 0
	v_mov_b32_e32 v65, 0
	v_mul_u32_u24_e32 v26, s28, v20
	v_add_lshl_u32 v26, v26, v21, 2
	s_lshl_b32 s0, s28, 7
	v_add_u32_e32 v27, s0, v26
	v_cmp_gt_i32_e32 vcc, s29, v21
	s_and_saveexec_b64 s[0:1], vcc
	global_load_dwordx4 v[58:61], v26, s[26:27]
	global_load_dwordx4 v[62:65], v27, s[26:27]
	s_mov_b64 exec, s[0:1]
	s_add_u32 s24, s24, s34
	s_sub_u32 s1, s24, 9600
	s_cmpk_lt_u32 s1, 3072
	s_cselect_b32 s1, 3072, 0
	s_add_u32 s24, s24, s1
	s_min_u32 s0, s24, 14015
	s_mov_b32 s21, s0
	s_mov_b32 s0, s21
	s_cmpk_lt_u32 s0, 9600
	s_cbranch_scc0 .Ltc1_c54
	s_and_b32 s1, s0, 31
	s_lshl_b32 s1, s1, 6
	s_lshr_b32 s21, s0, 5
	s_lshl_b32 s21, s21, 6
	s_movk_i32 s29, 64
	s_cmpk_lt_u32 s21, 7680
	s_cbranch_scc1 .Ltc1_n56
	s_cmpk_lt_u32 s21, 18944
	s_cbranch_scc0 .Ltc1_t55
	s_add_u32 s21, s21, 48
	s_branch .Ltc1_n56

; __device__ __forceinline__ void tconv_tile(LAS float* tile, const float* src, int ld, int k0, int n0, int mode, bf16_t* dst, int K) {
;     ...
;     for (int it = 0; it < 2; ++it) { const int idx = tid + it * 512, kk = idx >> 4, n4 = (idx & 15) * 4, nn = n0 + n4; int oc = nn; bool valid = true;
;         if (mode == 1) { if (nn < 7680) oc = nn; else if (nn < 18944) oc = nn + 48; else if (nn < INW) oc = 7680 + (nn - 18944); else valid = false; }
;         f32x4 v = (f32x4){0.f, 0.f, 0.f, 0.f}; if (valid) v = *(const f32x4*)(src + (size_t)(k0 + kk) * ld + oc);
; __device__ __forceinline__ void prologue(LAS unsigned char* lds, const Ctx& P, int l) {
;     ...
;     for (int t = blockIdx.x; t < T_ALL; t += G) {
;         int q = t;
;         if (q < T_IN) { const int kt = q & 31, ntl = q >> 5; tconv_tile(tile, P.in[3] + (size_t)l * DM * INW, INW, kt * 64, ntl * 64, 1, (bf16_t*)(ws + WS_WIN), DM); continue; }
.Ltc1_d53:
	v_mov_b32_e32 v78, 0
	v_mov_b32_e32 v79, 0
	v_mov_b32_e32 v80, 0
	v_mov_b32_e32 v81, 0
	v_mov_b32_e32 v82, 0
	v_mov_b32_e32 v83, 0
	v_mov_b32_e32 v84, 0
	v_mov_b32_e32 v85, 0
	v_mul_u32_u24_e32 v26, s28, v20
	v_add_lshl_u32 v26, v26, v21, 2
	s_lshl_b32 s0, s28, 7
	v_add_u32_e32 v27, s0, v26
	v_cmp_gt_i32_e32 vcc, s29, v21
	s_and_saveexec_b64 s[0:1], vcc
	global_load_dwordx4 v[78:81], v26, s[26:27]
	global_load_dwordx4 v[82:85], v27, s[26:27]
	s_mov_b64 exec, s[0:1]
	s_add_u32 s24, s24, s34
	s_sub_u32 s1, s24, 9600
	s_cmpk_lt_u32 s1, 3072
	s_cselect_b32 s1, 3072, 0
	s_add_u32 s24, s24, s1
	s_min_u32 s0, s24, 14015
	s_mov_b32 s21, s0
	s_mov_b32 s0, s21
	s_cmpk_lt_u32 s0, 9600
	s_cbranch_scc0 .Ltc1_c67
	s_and_b32 s1, s0, 31
	s_lshl_b32 s1, s1, 6
	s_lshr_b32 s21, s0, 5
	s_lshl_b32 s21, s21, 6
	s_movk_i32 s29, 64
	s_cmpk_lt_u32 s21, 7680
	s_cbranch_scc1 .Ltc1_n69
	s_cmpk_lt_u32 s21, 18944
	s_cbranch_scc0 .Ltc1_t68
	s_add_u32 s21, s21, 48
	s_branch .Ltc1_n69

; __device__ __forceinline__ unsigned cvt_pk_bf16(float lo, float hi) { unsigned r; asm("v_cvt_pk_bf16_f32 %0, %1, %2" : "=v"(r) : "v"(lo), "v"(hi)); return r; }
; __device__ __forceinline__ void tconv_tile(LAS float* tile, const float* src, int ld, int k0, int n0, int mode, bf16_t* dst, int K) {
;     ...
;     for (int it = 0; it < 2; ++it) { const int idx = tid + it * 512, kk = idx >> 4, n4 = (idx & 15) * 4, nn = n0 + n4; int oc = nn; bool valid = true;
;         if (mode == 1) { if (nn < 7680) oc = nn; else if (nn < 18944) oc = nn + 48; else if (nn < INW) oc = 7680 + (nn - 18944); else valid = false; }
;         f32x4 v = (f32x4){0.f, 0.f, 0.f, 0.f}; if (valid) v = *(const f32x4*)(src + (size_t)(k0 + kk) * ld + oc);
;         tile[kk * 65 + n4 + 0] = v[0]; tile[kk * 65 + n4 + 1] = v[1]; tile[kk * 65 + n4 + 2] = v[2]; tile[kk * 65 + n4 + 3] = v[3]; }
;     __syncthreads();
;     { const int n = tid >> 3, k8 = (tid & 7) * 8; float v[8];
; #pragma unroll
;         for (int e = 0; e < 8; ++e) v[e] = tile[(k8 + e) * 65 + n];
;         u32x4 w; w.x = cvt_pk_bf16(v[0], v[1]); w.y = cvt_pk_bf16(v[2], v[3]); w.z = cvt_pk_bf16(v[4], v[5]); w.w = cvt_pk_bf16(v[6], v[7]);
;         *(u32x4*)(dst + (size_t)(n0 + n) * K + k0 + k8) = w; }
; __device__ __forceinline__ void prologue(LAS unsigned char* lds, const Ctx& P, int l) {
;     ...
;     for (int t = blockIdx.x; t < T_ALL; t += G) {
;         int q = t;
;         if (q < T_IN) { const int kt = q & 31, ntl = q >> 5; tconv_tile(tile, P.in[3] + (size_t)l * DM * INW, INW, kt * 64, ntl * 64, 1, (bf16_t*)(ws + WS_WIN), DM); continue; }
.Ltc1_d66:
	v_mov_b32_e32 v86, 0
	v_mov_b32_e32 v87, 0
	v_mov_b32_e32 v88, 0
	v_mov_b32_e32 v89, 0
	v_mov_b32_e32 v90, 0
	v_mov_b32_e32 v91, 0
	v_mov_b32_e32 v92, 0
	v_mov_b32_e32 v93, 0
	v_mul_u32_u24_e32 v26, s28, v20
	v_add_lshl_u32 v26, v26, v21, 2
	s_lshl_b32 s0, s28, 7
	v_add_u32_e32 v27, s0, v26
	v_cmp_gt_i32_e32 vcc, s29, v21
	s_and_saveexec_b64 s[0:1], vcc
	global_load_dwordx4 v[86:89], v26, s[26:27]
	global_load_dwordx4 v[90:93], v27, s[26:27]
	s_mov_b64 exec, s[0:1]
	s_add_u32 s24, s24, s34
	s_sub_u32 s1, s24, 9600
	s_cmpk_lt_u32 s1, 3072
	s_cselect_b32 s1, 3072, 0
	s_add_u32 s24, s24, s1
	s_cmpk_ge_u32 s25, 14016
	s_cbranch_scc1 .Ltc1_exit
	s_waitcnt vmcnt(10)
	v_add_u32_e32 v28, 0, v22
	ds_write2_b32 v28, v34, v35 offset1:1
	ds_write2_b32 v28, v36, v37 offset0:2 offset1:3
	v_add_u32_e32 v28, 0x2080, v28
	ds_write2_b32 v28, v38, v39 offset1:1
	ds_write2_b32 v28, v40, v41 offset0:2 offset1:3
	s_mov_b32 s21, s25
	s_mov_b32 s0, s21
	s_cmpk_lt_u32 s0, 9600
	s_cbranch_scc0 .Ltc1_c80
	s_and_b32 s1, s0, 31
	s_lshl_b32 s1, s1, 6
	s_lshr_b32 s21, s0, 5
	s_lshl_b32 s21, s21, 17
	s_add_u32 s1, s1, s21
	s_lshl_b32 s1, s1, 1
	s_add_u32 s1, s1, 0x4001000
	s_add_u32 s30, s68, s1
	s_addc_u32 s31, s69, 0
	s_movk_i32 s20, 0x800
	s_branch .Ltc1_d79

; #define LAS __attribute__((address_space(3)))
; __device__ __forceinline__ unsigned cvt_pk_bf16(float lo, float hi) { unsigned r; asm("v_cvt_pk_bf16_f32 %0, %1, %2" : "=v"(r) : "v"(lo), "v"(hi)); return r; }
; __device__ __forceinline__ int opaque_tid() { int t = threadIdx.x; asm volatile("" : "+v"(t)); return t; }
; __device__ __forceinline__ void tconv_tile(LAS float* tile, const float* src, int ld, int k0, int n0, int mode, bf16_t* dst, int K) {
;     ...
;     { const int n = tid >> 3, k8 = (tid & 7) * 8; float v[8];
; #pragma unroll
;         for (int e = 0; e < 8; ++e) v[e] = tile[(k8 + e) * 65 + n];
;         u32x4 w; w.x = cvt_pk_bf16(v[0], v[1]); w.y = cvt_pk_bf16(v[2], v[3]); w.z = cvt_pk_bf16(v[4], v[5]); w.w = cvt_pk_bf16(v[6], v[7]);
;         *(u32x4*)(dst + (size_t)(n0 + n) * K + k0 + k8) = w; }
;     __syncthreads();
; }
; __device__ __forceinline__ void prologue(LAS unsigned char* lds, const Ctx& P, int l) {
;     unsigned char* ws = P.ws; LAS float* tile = (LAS float*)lds;
;     const int tid = opaque_tid(), G = gridDim.x;
;     const int T_IN = 32 * 300, T_BR = 4 * 512, T_OUT = 1024, T_MEM = 1024, T_W1 = 256, T_WA = 64;
;     const int T_ALL = T_IN + T_BR + T_OUT + T_MEM + T_W1 + T_WA;
;     for (int t = blockIdx.x; t < T_ALL; t += G) {
;         int q = t;
;         if (q < T_IN) { const int kt = q & 31, ntl = q >> 5; tconv_tile(tile, P.in[3] + (size_t)l * DM * INW, INW, kt * 64, ntl * 64, 1, (bf16_t*)(ws + WS_WIN), DM); continue; }
.Ltc1_d79:
	v_mul_u32_u24_e32 v29, s20, v24
	v_add_lshl_u32 v29, v29, v25, 1
	s_waitcnt lgkmcnt(0)
	s_barrier
	v_add_u32_e32 v28, 0, v23
	ds_read2_b32 v[2:3], v28 offset1:65
	ds_read2_b32 v[4:5], v28 offset0:130 offset1:195
	v_add_u32_e32 v28, 0x400, v28
	ds_read2_b32 v[6:7], v28 offset0:4 offset1:69
	ds_read2_b32 v[10:11], v28 offset0:134 offset1:199
	s_waitcnt lgkmcnt(3)
	v_cvt_pk_bf16_f32 v2, v2, v3
	s_waitcnt lgkmcnt(2)
	v_cvt_pk_bf16_f32 v3, v4, v5
	s_waitcnt lgkmcnt(1)
	v_cvt_pk_bf16_f32 v4, v6, v7
	s_waitcnt lgkmcnt(0)
	v_cvt_pk_bf16_f32 v5, v10, v11
	global_store_dwordx4 v29, v[2:5], s[30:31]
	s_add_u32 s25, s25, s34
	s_sub_u32 s1, s25, 9600
	s_cmpk_lt_u32 s1, 3072
	s_cselect_b32 s1, 3072, 0
	s_add_u32 s25, s25, s1
	s_min_u32 s0, s24, 14015
	s_mov_b32 s21, s0
	s_mov_b32 s0, s21
	s_cmpk_lt_u32 s0, 9600
	s_cbranch_scc0 .Ltc1_c87
	s_and_b32 s1, s0, 31
	s_lshl_b32 s1, s1, 6
	s_lshr_b32 s21, s0, 5
	s_lshl_b32 s21, s21, 6
	s_movk_i32 s29, 64
	s_cmpk_lt_u32 s21, 7680
	s_cbranch_scc1 .Ltc1_n89
	s_cmpk_lt_u32 s21, 18944
	s_cbranch_scc0 .Ltc1_t88
	s_add_u32 s21, s21, 48
	s_branch .Ltc1_n89

; #define LAS __attribute__((address_space(3)))
; __device__ __forceinline__ unsigned cvt_pk_bf16(float lo, float hi) { unsigned r; asm("v_cvt_pk_bf16_f32 %0, %1, %2" : "=v"(r) : "v"(lo), "v"(hi)); return r; }
; __device__ __forceinline__ int opaque_tid() { int t = threadIdx.x; asm volatile("" : "+v"(t)); return t; }
; __device__ __forceinline__ void tconv_tile(LAS float* tile, const float* src, int ld, int k0, int n0, int mode, bf16_t* dst, int K) {
;     ...
;     for (int it = 0; it < 2; ++it) { const int idx = tid + it * 512, kk = idx >> 4, n4 = (idx & 15) * 4, nn = n0 + n4; int oc = nn; bool valid = true;
;         if (mode == 1) { if (nn < 7680) oc = nn; else if (nn < 18944) oc = nn + 48; else if (nn < INW) oc = 7680 + (nn - 18944); else valid = false; }
;         f32x4 v = (f32x4){0.f, 0.f, 0.f, 0.f}; if (valid) v = *(const f32x4*)(src + (size_t)(k0 + kk) * ld + oc);
;         tile[kk * 65 + n4 + 0] = v[0]; tile[kk * 65 + n4 + 1] = v[1]; tile[kk * 65 + n4 + 2] = v[2]; tile[kk * 65 + n4 + 3] = v[3]; }
;     __syncthreads();
;     { const int n = tid >> 3, k8 = (tid & 7) * 8; float v[8];
; #pragma unroll
;         for (int e = 0; e < 8; ++e) v[e] = tile[(k8 + e) * 65 + n];
;         u32x4 w; w.x = cvt_pk_bf16(v[0], v[1]); w.y = cvt_pk_bf16(v[2], v[3]); w.z = cvt_pk_bf16(v[4], v[5]); w.w = cvt_pk_bf16(v[6], v[7]);
;         *(u32x4*)(dst + (size_t)(n0 + n) * K + k0 + k8) = w; }
;     __syncthreads();
; }
; __device__ __forceinline__ void prologue(LAS unsigned char* lds, const Ctx& P, int l) {
;     unsigned char* ws = P.ws; LAS float* tile = (LAS float*)lds;
;     const int tid = opaque_tid(), G = gridDim.x;
;     const int T_IN = 32 * 300, T_BR = 4 * 512, T_OUT = 1024, T_MEM = 1024, T_W1 = 256, T_WA = 64;
;     const int T_ALL = T_IN + T_BR + T_OUT + T_MEM + T_W1 + T_WA;
;     for (int t = blockIdx.x; t < T_ALL; t += G) {
;         int q = t;
;         if (q < T_IN) { const int kt = q & 31, ntl = q >> 5; tconv_tile(tile, P.in[3] + (size_t)l * DM * INW, INW, kt * 64, ntl * 64, 1, (bf16_t*)(ws + WS_WIN), DM); continue; }
.Ltc1_d86:
	v_mov_b32_e32 v34, 0
	v_mov_b32_e32 v35, 0
	v_mov_b32_e32 v36, 0
	v_mov_b32_e32 v37, 0
	v_mov_b32_e32 v38, 0
	v_mov_b32_e32 v39, 0
	v_mov_b32_e32 v40, 0
	v_mov_b32_e32 v41, 0
	v_mul_u32_u24_e32 v26, s28, v20
	v_add_lshl_u32 v26, v26, v21, 2
	s_lshl_b32 s0, s28, 7
	v_add_u32_e32 v27, s0, v26
	v_cmp_gt_i32_e32 vcc, s29, v21
	s_and_saveexec_b64 s[0:1], vcc
	global_load_dwordx4 v[34:37], v26, s[26:27]
	global_load_dwordx4 v[38:41], v27, s[26:27]
	s_mov_b64 exec, s[0:1]
	s_add_u32 s24, s24, s34
	s_sub_u32 s1, s24, 9600
	s_cmpk_lt_u32 s1, 3072
	s_cselect_b32 s1, 3072, 0
	s_add_u32 s24, s24, s1
	s_cmpk_ge_u32 s25, 14016
	s_cbranch_scc1 .Ltc1_exit
	s_waitcnt vmcnt(11)
	v_add_u32_e32 v28, 16896, v22
	ds_write2_b32 v28, v42, v43 offset1:1
	ds_write2_b32 v28, v44, v45 offset0:2 offset1:3
	v_add_u32_e32 v28, 0x2080, v28
	ds_write2_b32 v28, v46, v47 offset1:1
	ds_write2_b32 v28, v48, v49 offset0:2 offset1:3
	s_mov_b32 s21, s25
	s_mov_b32 s0, s21
	s_cmpk_lt_u32 s0, 9600
	s_cbranch_scc0 .Ltc1_c100
	s_and_b32 s1, s0, 31
	s_lshl_b32 s1, s1, 6
	s_lshr_b32 s21, s0, 5
	s_lshl_b32 s21, s21, 17
	s_add_u32 s1, s1, s21
	s_lshl_b32 s1, s1, 1
	s_add_u32 s1, s1, 0x4001000
	s_add_u32 s30, s68, s1
	s_addc_u32 s31, s69, 0
	s_movk_i32 s20, 0x800
	s_branch .Ltc1_d99

; #define LAS __attribute__((address_space(3)))
; __device__ __forceinline__ unsigned cvt_pk_bf16(float lo, float hi) { unsigned r; asm("v_cvt_pk_bf16_f32 %0, %1, %2" : "=v"(r) : "v"(lo), "v"(hi)); return r; }
; __device__ __forceinline__ int opaque_tid() { int t = threadIdx.x; asm volatile("" : "+v"(t)); return t; }
; __device__ __forceinline__ void tconv_tile(LAS float* tile, const float* src, int ld, int k0, int n0, int mode, bf16_t* dst, int K) {
;     ...
;     { const int n = tid >> 3, k8 = (tid & 7) * 8; float v[8];
; #pragma unroll
;         for (int e = 0; e < 8; ++e) v[e] = tile[(k8 + e) * 65 + n];
;         u32x4 w; w.x = cvt_pk_bf16(v[0], v[1]); w.y = cvt_pk_bf16(v[2], v[3]); w.z = cvt_pk_bf16(v[4], v[5]); w.w = cvt_pk_bf16(v[6], v[7]);
;         *(u32x4*)(dst + (size_t)(n0 + n) * K + k0 + k8) = w; }
;     __syncthreads();
; }
; __device__ __forceinline__ void prologue(LAS unsigned char* lds, const Ctx& P, int l) {
;     unsigned char* ws = P.ws; LAS float* tile = (LAS float*)lds;
;     const int tid = opaque_tid(), G = gridDim.x;
;     const int T_IN = 32 * 300, T_BR = 4 * 512, T_OUT = 1024, T_MEM = 1024, T_W1 = 256, T_WA = 64;
;     const int T_ALL = T_IN + T_BR + T_OUT + T_MEM + T_W1 + T_WA;
;     for (int t = blockIdx.x; t < T_ALL; t += G) {
;         int q = t;
;         if (q < T_IN) { const int kt = q & 31, ntl = q >> 5; tconv_tile(tile, P.in[3] + (size_t)l * DM * INW, INW, kt * 64, ntl * 64, 1, (bf16_t*)(ws + WS_WIN), DM); continue; }
.Ltc1_d99:
	v_mul_u32_u24_e32 v29, s20, v24
	v_add_lshl_u32 v29, v29, v25, 1
	s_waitcnt lgkmcnt(0)
	s_barrier
	v_add_u32_e32 v28, 16896, v23
	ds_read2_b32 v[2:3], v28 offset1:65
	ds_read2_b32 v[4:5], v28 offset0:130 offset1:195
	v_add_u32_e32 v28, 0x400, v28
	ds_read2_b32 v[6:7], v28 offset0:4 offset1:69
	ds_read2_b32 v[10:11], v28 offset0:134 offset1:199
	s_waitcnt lgkmcnt(3)
	v_cvt_pk_bf16_f32 v2, v2, v3
	s_waitcnt lgkmcnt(2)
	v_cvt_pk_bf16_f32 v3, v4, v5
	s_waitcnt lgkmcnt(1)
	v_cvt_pk_bf16_f32 v4, v6, v7
	s_waitcnt lgkmcnt(0)
	v_cvt_pk_bf16_f32 v5, v10, v11
	global_store_dwordx4 v29, v[2:5], s[30:31]
	s_add_u32 s25, s25, s34
	s_sub_u32 s1, s25, 9600
	s_cmpk_lt_u32 s1, 3072
	s_cselect_b32 s1, 3072, 0
	s_add_u32 s25, s25, s1
	s_min_u32 s0, s24, 14015
	s_mov_b32 s21, s0
	s_mov_b32 s0, s21
	s_cmpk_lt_u32 s0, 9600
	s_cbranch_scc0 .Ltc1_c107
	s_and_b32 s1, s0, 31
	s_lshl_b32 s1, s1, 6
	s_lshr_b32 s21, s0, 5
	s_lshl_b32 s21, s21, 6
	s_movk_i32 s29, 64
	s_cmpk_lt_u32 s21, 7680
	s_cbranch_scc1 .Ltc1_n109
	s_cmpk_lt_u32 s21, 18944
	s_cbranch_scc0 .Ltc1_t108
	s_add_u32 s21, s21, 48
	s_branch .Ltc1_n109

; #define LAS __attribute__((address_space(3)))
; __device__ __forceinline__ unsigned cvt_pk_bf16(float lo, float hi) { unsigned r; asm("v_cvt_pk_bf16_f32 %0, %1, %2" : "=v"(r) : "v"(lo), "v"(hi)); return r; }
; __device__ __forceinline__ int opaque_tid() { int t = threadIdx.x; asm volatile("" : "+v"(t)); return t; }
; __device__ __forceinline__ void tconv_tile(LAS float* tile, const float* src, int ld, int k0, int n0, int mode, bf16_t* dst, int K) {
;     ...
;     for (int it = 0; it < 2; ++it) { const int idx = tid + it * 512, kk = idx >> 4, n4 = (idx & 15) * 4, nn = n0 + n4; int oc = nn; bool valid = true;
;         if (mode == 1) { if (nn < 7680) oc = nn; else if (nn < 18944) oc = nn + 48; else if (nn < INW) oc = 7680 + (nn - 18944); else valid = false; }
;         f32x4 v = (f32x4){0.f, 0.f, 0.f, 0.f}; if (valid) v = *(const f32x4*)(src + (size_t)(k0 + kk) * ld + oc);
;         tile[kk * 65 + n4 + 0] = v[0]; tile[kk * 65 + n4 + 1] = v[1]; tile[kk * 65 + n4 + 2] = v[2]; tile[kk * 65 + n4 + 3] = v[3]; }
;     __syncthreads();
;     { const int n = tid >> 3, k8 = (tid & 7) * 8; float v[8];
; #pragma unroll
;         for (int e = 0; e < 8; ++e) v[e] = tile[(k8 + e) * 65 + n];
;         u32x4 w; w.x = cvt_pk_bf16(v[0], v[1]); w.y = cvt_pk_bf16(v[2], v[3]); w.z = cvt_pk_bf16(v[4], v[5]); w.w = cvt_pk_bf16(v[6], v[7]);
;         *(u32x4*)(dst + (size_t)(n0 + n) * K + k0 + k8) = w; }
;     __syncthreads();
; }
; __device__ __forceinline__ void prologue(LAS unsigned char* lds, const Ctx& P, int l) {
;     unsigned char* ws = P.ws; LAS float* tile = (LAS float*)lds;
;     const int tid = opaque_tid(), G = gridDim.x;
;     const int T_IN = 32 * 300, T_BR = 4 * 512, T_OUT = 1024, T_MEM = 1024, T_W1 = 256, T_WA = 64;
;     const int T_ALL = T_IN + T_BR + T_OUT + T_MEM + T_W1 + T_WA;
;     for (int t = blockIdx.x; t < T_ALL; t += G) {
;         int q = t;
;         if (q < T_IN) { const int kt = q & 31, ntl = q >> 5; tconv_tile(tile, P.in[3] + (size_t)l * DM * INW, INW, kt * 64, ntl * 64, 1, (bf16_t*)(ws + WS_WIN), DM); continue; }
.Ltc1_d106:
	v_mov_b32_e32 v42, 0
	v_mov_b32_e32 v43, 0
	v_mov_b32_e32 v44, 0
	v_mov_b32_e32 v45, 0
	v_mov_b32_e32 v46, 0
	v_mov_b32_e32 v47, 0
	v_mov_b32_e32 v48, 0
	v_mov_b32_e32 v49, 0
	v_mul_u32_u24_e32 v26, s28, v20
	v_add_lshl_u32 v26, v26, v21, 2
	s_lshl_b32 s0, s28, 7
	v_add_u32_e32 v27, s0, v26
	v_cmp_gt_i32_e32 vcc, s29, v21
	s_and_saveexec_b64 s[0:1], vcc
	global_load_dwordx4 v[42:45], v26, s[26:27]
	global_load_dwordx4 v[46:49], v27, s[26:27]
	s_mov_b64 exec, s[0:1]
	s_add_u32 s24, s24, s34
	s_sub_u32 s1, s24, 9600
	s_cmpk_lt_u32 s1, 3072
	s_cselect_b32 s1, 3072, 0
	s_add_u32 s24, s24, s1
	s_cmpk_ge_u32 s25, 14016
	s_cbranch_scc1 .Ltc1_exit
	s_waitcnt vmcnt(12)
	v_add_u32_e32 v28, 0, v22
	ds_write2_b32 v28, v50, v51 offset1:1
	ds_write2_b32 v28, v52, v53 offset0:2 offset1:3
	v_add_u32_e32 v28, 0x2080, v28
	ds_write2_b32 v28, v54, v55 offset1:1
	ds_write2_b32 v28, v56, v57 offset0:2 offset1:3
	s_mov_b32 s21, s25
	s_mov_b32 s0, s21
	s_cmpk_lt_u32 s0, 9600
	s_cbranch_scc0 .Ltc1_c120
	s_and_b32 s1, s0, 31
	s_lshl_b32 s1, s1, 6
	s_lshr_b32 s21, s0, 5
	s_lshl_b32 s21, s21, 17
	s_add_u32 s1, s1, s21
	s_lshl_b32 s1, s1, 1
	s_add_u32 s1, s1, 0x4001000
	s_add_u32 s30, s68, s1
	s_addc_u32 s31, s69, 0
	s_movk_i32 s20, 0x800
	s_branch .Ltc1_d119

; #define LAS __attribute__((address_space(3)))
; __device__ __forceinline__ unsigned cvt_pk_bf16(float lo, float hi) { unsigned r; asm("v_cvt_pk_bf16_f32 %0, %1, %2" : "=v"(r) : "v"(lo), "v"(hi)); return r; }
; __device__ __forceinline__ int opaque_tid() { int t = threadIdx.x; asm volatile("" : "+v"(t)); return t; }
; __device__ __forceinline__ void tconv_tile(LAS float* tile, const float* src, int ld, int k0, int n0, int mode, bf16_t* dst, int K) {
;     ...
;     for (int it = 0; it < 2; ++it) { const int idx = tid + it * 512, kk = idx >> 4, n4 = (idx & 15) * 4, nn = n0 + n4; int oc = nn; bool valid = true;
;         if (mode == 1) { if (nn < 7680) oc = nn; else if (nn < 18944) oc = nn + 48; else if (nn < INW) oc = 7680 + (nn - 18944); else valid = false; }
;         f32x4 v = (f32x4){0.f, 0.f, 0.f, 0.f}; if (valid) v = *(const f32x4*)(src + (size_t)(k0 + kk) * ld + oc);
;         tile[kk * 65 + n4 + 0] = v[0]; tile[kk * 65 + n4 + 1] = v[1]; tile[kk * 65 + n4 + 2] = v[2]; tile[kk * 65 + n4 + 3] = v[3]; }
;     __syncthreads();
;     { const int n = tid >> 3, k8 = (tid & 7) * 8; float v[8];
; #pragma unroll
;         for (int e = 0; e < 8; ++e) v[e] = tile[(k8 + e) * 65 + n];
;         u32x4 w; w.x = cvt_pk_bf16(v[0], v[1]); w.y = cvt_pk_bf16(v[2], v[3]); w.z = cvt_pk_bf16(v[4], v[5]); w.w = cvt_pk_bf16(v[6], v[7]);
;         *(u32x4*)(dst + (size_t)(n0 + n) * K + k0 + k8) = w; }
;     __syncthreads();
; }
; __device__ __forceinline__ void prologue(LAS unsigned char* lds, const Ctx& P, int l) {
;     unsigned char* ws = P.ws; LAS float* tile = (LAS float*)lds;
;     const int tid = opaque_tid(), G = gridDim.x;
;     const int T_IN = 32 * 300, T_BR = 4 * 512, T_OUT = 1024, T_MEM = 1024, T_W1 = 256, T_WA = 64;
;     const int T_ALL = T_IN + T_BR + T_OUT + T_MEM + T_W1 + T_WA;
;     for (int t = blockIdx.x; t < T_ALL; t += G) {
;         int q = t;
;         if (q < T_IN) { const int kt = q & 31, ntl = q >> 5; tconv_tile(tile, P.in[3] + (size_t)l * DM * INW, INW, kt * 64, ntl * 64, 1, (bf16_t*)(ws + WS_WIN), DM); continue; }
.Ltc1_d126:
	v_mov_b32_e32 v50, 0
	v_mov_b32_e32 v51, 0
	v_mov_b32_e32 v52, 0
	v_mov_b32_e32 v53, 0
	v_mov_b32_e32 v54, 0
	v_mov_b32_e32 v55, 0
	v_mov_b32_e32 v56, 0
	v_mov_b32_e32 v57, 0
	v_mul_u32_u24_e32 v26, s28, v20
	v_add_lshl_u32 v26, v26, v21, 2
	s_lshl_b32 s0, s28, 7
	v_add_u32_e32 v27, s0, v26
	v_cmp_gt_i32_e32 vcc, s29, v21
	s_and_saveexec_b64 s[0:1], vcc
	global_load_dwordx4 v[50:53], v26, s[26:27]
	global_load_dwordx4 v[54:57], v27, s[26:27]
	s_mov_b64 exec, s[0:1]
	s_add_u32 s24, s24, s34
	s_sub_u32 s1, s24, 9600
	s_cmpk_lt_u32 s1, 3072
	s_cselect_b32 s1, 3072, 0
	s_add_u32 s24, s24, s1
	s_cmpk_ge_u32 s25, 14016
	s_cbranch_scc1 .Ltc1_exit
	s_waitcnt vmcnt(13)
	v_add_u32_e32 v28, 16896, v22
	ds_write2_b32 v28, v58, v59 offset1:1
	ds_write2_b32 v28, v60, v61 offset0:2 offset1:3
	v_add_u32_e32 v28, 0x2080, v28
	ds_write2_b32 v28, v62, v63 offset1:1
	ds_write2_b32 v28, v64, v65 offset0:2 offset1:3
	s_mov_b32 s21, s25
	s_mov_b32 s0, s21
	s_cmpk_lt_u32 s0, 9600
	s_cbranch_scc0 .Ltc1_c140
	s_and_b32 s1, s0, 31
	s_lshl_b32 s1, s1, 6
	s_lshr_b32 s21, s0, 5
	s_lshl_b32 s21, s21, 17
	s_add_u32 s1, s1, s21
	s_lshl_b32 s1, s1, 1
	s_add_u32 s1, s1, 0x4001000
	s_add_u32 s30, s68, s1
	s_addc_u32 s31, s69, 0
	s_movk_i32 s20, 0x800
	s_branch .Ltc1_d139

; #define LAS __attribute__((address_space(3)))
; __device__ __forceinline__ unsigned cvt_pk_bf16(float lo, float hi) { unsigned r; asm("v_cvt_pk_bf16_f32 %0, %1, %2" : "=v"(r) : "v"(lo), "v"(hi)); return r; }
; __device__ __forceinline__ int opaque_tid() { int t = threadIdx.x; asm volatile("" : "+v"(t)); return t; }
; __device__ __forceinline__ void tconv_tile(LAS float* tile, const float* src, int ld, int k0, int n0, int mode, bf16_t* dst, int K) {
;     ...
;     for (int it = 0; it < 2; ++it) { const int idx = tid + it * 512, kk = idx >> 4, n4 = (idx & 15) * 4, nn = n0 + n4; int oc = nn; bool valid = true;
;         if (mode == 1) { if (nn < 7680) oc = nn; else if (nn < 18944) oc = nn + 48; else if (nn < INW) oc = 7680 + (nn - 18944); else valid = false; }
;         f32x4 v = (f32x4){0.f, 0.f, 0.f, 0.f}; if (valid) v = *(const f32x4*)(src + (size_t)(k0 + kk) * ld + oc);
;         tile[kk * 65 + n4 + 0] = v[0]; tile[kk * 65 + n4 + 1] = v[1]; tile[kk * 65 + n4 + 2] = v[2]; tile[kk * 65 + n4 + 3] = v[3]; }
;     __syncthreads();
;     { const int n = tid >> 3, k8 = (tid & 7) * 8; float v[8];
; #pragma unroll
;         for (int e = 0; e < 8; ++e) v[e] = tile[(k8 + e) * 65 + n];
;         u32x4 w; w.x = cvt_pk_bf16(v[0], v[1]); w.y = cvt_pk_bf16(v[2], v[3]); w.z = cvt_pk_bf16(v[4], v[5]); w.w = cvt_pk_bf16(v[6], v[7]);
;         *(u32x4*)(dst + (size_t)(n0 + n) * K + k0 + k8) = w; }
;     __syncthreads();
; }
; __device__ __forceinline__ void prologue(LAS unsigned char* lds, const Ctx& P, int l) {
;     unsigned char* ws = P.ws; LAS float* tile = (LAS float*)lds;
;     const int tid = opaque_tid(), G = gridDim.x;
;     const int T_IN = 32 * 300, T_BR = 4 * 512, T_OUT = 1024, T_MEM = 1024, T_W1 = 256, T_WA = 64;
;     const int T_ALL = T_IN + T_BR + T_OUT + T_MEM + T_W1 + T_WA;
;     for (int t = blockIdx.x; t < T_ALL; t += G) {
;         int q = t;
;         if (q < T_IN) { const int kt = q & 31, ntl = q >> 5; tconv_tile(tile, P.in[3] + (size_t)l * DM * INW, INW, kt * 64, ntl * 64, 1, (bf16_t*)(ws + WS_WIN), DM); continue; }
.Ltc1_d146:
	v_mov_b32_e32 v58, 0
	v_mov_b32_e32 v59, 0
	v_mov_b32_e32 v60, 0
	v_mov_b32_e32 v61, 0
	v_mov_b32_e32 v62, 0
	v_mov_b32_e32 v63, 0
	v_mov_b32_e32 v64, 0
	v_mov_b32_e32 v65, 0
	v_mul_u32_u24_e32 v26, s28, v20
	v_add_lshl_u32 v26, v26, v21, 2
	s_lshl_b32 s0, s28, 7
	v_add_u32_e32 v27, s0, v26
	v_cmp_gt_i32_e32 vcc, s29, v21
	s_and_saveexec_b64 s[0:1], vcc
	global_load_dwordx4 v[58:61], v26, s[26:27]
	global_load_dwordx4 v[62:65], v27, s[26:27]
	s_mov_b64 exec, s[0:1]
	s_add_u32 s24, s24, s34
	s_sub_u32 s1, s24, 9600
	s_cmpk_lt_u32 s1, 3072
	s_cselect_b32 s1, 3072, 0
	s_add_u32 s24, s24, s1
	s_cmpk_ge_u32 s25, 14016
	s_cbranch_scc1 .Ltc1_exit
	s_waitcnt vmcnt(14)
	v_add_u32_e32 v28, 0, v22
	ds_write2_b32 v28, v78, v79 offset1:1
	ds_write2_b32 v28, v80, v81 offset0:2 offset1:3
	v_add_u32_e32 v28, 0x2080, v28
	ds_write2_b32 v28, v82, v83 offset1:1
	ds_write2_b32 v28, v84, v85 offset0:2 offset1:3
	s_mov_b32 s21, s25
	s_mov_b32 s0, s21
	s_cmpk_lt_u32 s0, 9600
	s_cbranch_scc0 .Ltc1_c160
	s_and_b32 s1, s0, 31
	s_lshl_b32 s1, s1, 6
	s_lshr_b32 s21, s0, 5
	s_lshl_b32 s21, s21, 17
	s_add_u32 s1, s1, s21
	s_lshl_b32 s1, s1, 1
	s_add_u32 s1, s1, 0x4001000
	s_add_u32 s30, s68, s1
	s_addc_u32 s31, s69, 0
	s_movk_i32 s20, 0x800
	s_branch .Ltc1_d159

; #define LAS __attribute__((address_space(3)))
; __device__ __forceinline__ unsigned cvt_pk_bf16(float lo, float hi) { unsigned r; asm("v_cvt_pk_bf16_f32 %0, %1, %2" : "=v"(r) : "v"(lo), "v"(hi)); return r; }
; __device__ __forceinline__ int opaque_tid() { int t = threadIdx.x; asm volatile("" : "+v"(t)); return t; }
; __device__ __forceinline__ void tconv_tile(LAS float* tile, const float* src, int ld, int k0, int n0, int mode, bf16_t* dst, int K) {
;     ...
;     for (int it = 0; it < 2; ++it) { const int idx = tid + it * 512, kk = idx >> 4, n4 = (idx & 15) * 4, nn = n0 + n4; int oc = nn; bool valid = true;
;         if (mode == 1) { if (nn < 7680) oc = nn; else if (nn < 18944) oc = nn + 48; else if (nn < INW) oc = 7680 + (nn - 18944); else valid = false; }
;         f32x4 v = (f32x4){0.f, 0.f, 0.f, 0.f}; if (valid) v = *(const f32x4*)(src + (size_t)(k0 + kk) * ld + oc);
;         tile[kk * 65 + n4 + 0] = v[0]; tile[kk * 65 + n4 + 1] = v[1]; tile[kk * 65 + n4 + 2] = v[2]; tile[kk * 65 + n4 + 3] = v[3]; }
;     __syncthreads();
;     { const int n = tid >> 3, k8 = (tid & 7) * 8; float v[8];
; #pragma unroll
;         for (int e = 0; e < 8; ++e) v[e] = tile[(k8 + e) * 65 + n];
;         u32x4 w; w.x = cvt_pk_bf16(v[0], v[1]); w.y = cvt_pk_bf16(v[2], v[3]); w.z = cvt_pk_bf16(v[4], v[5]); w.w = cvt_pk_bf16(v[6], v[7]);
;         *(u32x4*)(dst + (size_t)(n0 + n) * K + k0 + k8) = w; }
;     __syncthreads();
; }
; __device__ __forceinline__ void prologue(LAS unsigned char* lds, const Ctx& P, int l) {
;     unsigned char* ws = P.ws; LAS float* tile = (LAS float*)lds;
;     const int tid = opaque_tid(), G = gridDim.x;
;     const int T_IN = 32 * 300, T_BR = 4 * 512, T_OUT = 1024, T_MEM = 1024, T_W1 = 256, T_WA = 64;
;     const int T_ALL = T_IN + T_BR + T_OUT + T_MEM + T_W1 + T_WA;
;     for (int t = blockIdx.x; t < T_ALL; t += G) {
;         int q = t;
;         if (q < T_IN) { const int kt = q & 31, ntl = q >> 5; tconv_tile(tile, P.in[3] + (size_t)l * DM * INW, INW, kt * 64, ntl * 64, 1, (bf16_t*)(ws + WS_WIN), DM); continue; }
.Ltc1_d166:
	v_mov_b32_e32 v78, 0
	v_mov_b32_e32 v79, 0
	v_mov_b32_e32 v80, 0
	v_mov_b32_e32 v81, 0
	v_mov_b32_e32 v82, 0
	v_mov_b32_e32 v83, 0
	v_mov_b32_e32 v84, 0
	v_mov_b32_e32 v85, 0
	v_mul_u32_u24_e32 v26, s28, v20
	v_add_lshl_u32 v26, v26, v21, 2
	s_lshl_b32 s0, s28, 7
	v_add_u32_e32 v27, s0, v26
	v_cmp_gt_i32_e32 vcc, s29, v21
	s_and_saveexec_b64 s[0:1], vcc
	global_load_dwordx4 v[78:81], v26, s[26:27]
	global_load_dwordx4 v[82:85], v27, s[26:27]
	s_mov_b64 exec, s[0:1]
	s_add_u32 s24, s24, s34
	s_sub_u32 s1, s24, 9600
	s_cmpk_lt_u32 s1, 3072
	s_cselect_b32 s1, 3072, 0
	s_add_u32 s24, s24, s1
	s_cmpk_ge_u32 s25, 14016
	s_cbranch_scc1 .Ltc1_exit
	s_waitcnt vmcnt(15)
	v_add_u32_e32 v28, 16896, v22
	ds_write2_b32 v28, v86, v87 offset1:1
	ds_write2_b32 v28, v88, v89 offset0:2 offset1:3
	v_add_u32_e32 v28, 0x2080, v28
	ds_write2_b32 v28, v90, v91 offset1:1
	ds_write2_b32 v28, v92, v93 offset0:2 offset1:3
	s_mov_b32 s21, s25
	s_mov_b32 s0, s21
	s_cmpk_lt_u32 s0, 9600
	s_cbranch_scc0 .Ltc1_c180
	s_and_b32 s1, s0, 31
	s_lshl_b32 s1, s1, 6
	s_lshr_b32 s21, s0, 5
	s_lshl_b32 s21, s21, 17
	s_add_u32 s1, s1, s21
	s_lshl_b32 s1, s1, 1
	s_add_u32 s1, s1, 0x4001000
	s_add_u32 s30, s68, s1
	s_addc_u32 s31, s69, 0
	s_movk_i32 s20, 0x800
	s_branch .Ltc1_d179

; __device__ __forceinline__ void tconv_tile(LAS float* tile, const float* src, int ld, int k0, int n0, int mode, bf16_t* dst, int K) {
;     ...
;     for (int it = 0; it < 2; ++it) { const int idx = tid + it * 512, kk = idx >> 4, n4 = (idx & 15) * 4, nn = n0 + n4; int oc = nn; bool valid = true;
;         if (mode == 1) { if (nn < 7680) oc = nn; else if (nn < 18944) oc = nn + 48; else if (nn < INW) oc = 7680 + (nn - 18944); else valid = false; }
;         f32x4 v = (f32x4){0.f, 0.f, 0.f, 0.f}; if (valid) v = *(const f32x4*)(src + (size_t)(k0 + kk) * ld + oc);
; __device__ __forceinline__ void prologue(LAS unsigned char* lds, const Ctx& P, int l) {
;     ...
;     for (int t = blockIdx.x; t < T_ALL; t += G) {
.Ltc1_d186:
	v_mov_b32_e32 v86, 0
	v_mov_b32_e32 v87, 0
	v_mov_b32_e32 v88, 0
	v_mov_b32_e32 v89, 0
	v_mov_b32_e32 v90, 0
	v_mov_b32_e32 v91, 0
	v_mov_b32_e32 v92, 0
	v_mov_b32_e32 v93, 0
	v_mul_u32_u24_e32 v26, s28, v20
	v_add_lshl_u32 v26, v26, v21, 2
	s_lshl_b32 s0, s28, 7
	v_add_u32_e32 v27, s0, v26
	v_cmp_gt_i32_e32 vcc, s29, v21
	s_and_saveexec_b64 s[0:1], vcc
	global_load_dwordx4 v[86:89], v26, s[26:27]
	global_load_dwordx4 v[90:93], v27, s[26:27]
	s_mov_b64 exec, s[0:1]
	s_add_u32 s24, s24, s34
	s_sub_u32 s1, s24, 9600
	s_cmpk_lt_u32 s1, 3072
	s_cselect_b32 s1, 3072, 0
	s_add_u32 s24, s24, s1

; #define LAS __attribute__((address_space(3)))
; __device__ __forceinline__ unsigned cvt_pk_bf16(float lo, float hi) { unsigned r; asm("v_cvt_pk_bf16_f32 %0, %1, %2" : "=v"(r) : "v"(lo), "v"(hi)); return r; }
; __device__ __forceinline__ int opaque_tid() { int t = threadIdx.x; asm volatile("" : "+v"(t)); return t; }
; __device__ __forceinline__ void tconv_tile(LAS float* tile, const float* src, int ld, int k0, int n0, int mode, bf16_t* dst, int K) {
;     ...
;     for (int it = 0; it < 2; ++it) { const int idx = tid + it * 512, kk = idx >> 4, n4 = (idx & 15) * 4, nn = n0 + n4; int oc = nn; bool valid = true;
;         if (mode == 1) { if (nn < 7680) oc = nn; else if (nn < 18944) oc = nn + 48; else if (nn < INW) oc = 7680 + (nn - 18944); else valid = false; }
;         f32x4 v = (f32x4){0.f, 0.f, 0.f, 0.f}; if (valid) v = *(const f32x4*)(src + (size_t)(k0 + kk) * ld + oc);
;         tile[kk * 65 + n4 + 0] = v[0]; tile[kk * 65 + n4 + 1] = v[1]; tile[kk * 65 + n4 + 2] = v[2]; tile[kk * 65 + n4 + 3] = v[3]; }
;     __syncthreads();
;     { const int n = tid >> 3, k8 = (tid & 7) * 8; float v[8];
; #pragma unroll
;         for (int e = 0; e < 8; ++e) v[e] = tile[(k8 + e) * 65 + n];
;         u32x4 w; w.x = cvt_pk_bf16(v[0], v[1]); w.y = cvt_pk_bf16(v[2], v[3]); w.z = cvt_pk_bf16(v[4], v[5]); w.w = cvt_pk_bf16(v[6], v[7]);
;         *(u32x4*)(dst + (size_t)(n0 + n) * K + k0 + k8) = w; }
;     __syncthreads();
; }
; __device__ __forceinline__ void prologue(LAS unsigned char* lds, const Ctx& P, int l) {
;     unsigned char* ws = P.ws; LAS float* tile = (LAS float*)lds;
;     const int tid = opaque_tid(), G = gridDim.x;
;     const int T_IN = 32 * 300, T_BR = 4 * 512, T_OUT = 1024, T_MEM = 1024, T_W1 = 256, T_WA = 64;
;     const int T_ALL = T_IN + T_BR + T_OUT + T_MEM + T_W1 + T_WA;
;     for (int t = blockIdx.x; t < T_ALL; t += G) {
;         int q = t;
;         if (q < T_IN) { const int kt = q & 31, ntl = q >> 5; tconv_tile(tile, P.in[3] + (size_t)l * DM * INW, INW, kt * 64, ntl * 64, 1, (bf16_t*)(ws + WS_WIN), DM); continue; }
.Ltc1_d206:
	v_mov_b32_e32 v34, 0
	v_mov_b32_e32 v35, 0
	v_mov_b32_e32 v36, 0
	v_mov_b32_e32 v37, 0
	v_mov_b32_e32 v38, 0
	v_mov_b32_e32 v39, 0
	v_mov_b32_e32 v40, 0
	v_mov_b32_e32 v41, 0
	v_mul_u32_u24_e32 v26, s28, v20
	v_add_lshl_u32 v26, v26, v21, 2
	s_lshl_b32 s0, s28, 7
	v_add_u32_e32 v27, s0, v26
	v_cmp_gt_i32_e32 vcc, s29, v21
	s_and_saveexec_b64 s[0:1], vcc
	global_load_dwordx4 v[34:37], v26, s[26:27]
	global_load_dwordx4 v[38:41], v27, s[26:27]
	s_mov_b64 exec, s[0:1]
	s_add_u32 s24, s24, s34
	s_sub_u32 s1, s24, 9600
	s_cmpk_lt_u32 s1, 3072
	s_cselect_b32 s1, 3072, 0
	s_add_u32 s24, s24, s1
	s_cmpk_ge_u32 s25, 14016
	s_cbranch_scc1 .Ltc1_exit
	s_waitcnt vmcnt(15)
	v_add_u32_e32 v28, 16896, v22
	ds_write2_b32 v28, v42, v43 offset1:1
	ds_write2_b32 v28, v44, v45 offset0:2 offset1:3
	v_add_u32_e32 v28, 0x2080, v28
	ds_write2_b32 v28, v46, v47 offset1:1
	ds_write2_b32 v28, v48, v49 offset0:2 offset1:3
	s_mov_b32 s21, s25
	s_mov_b32 s0, s21
	s_cmpk_lt_u32 s0, 9600
	s_cbranch_scc0 .Ltc1_c220
	s_and_b32 s1, s0, 31
	s_lshl_b32 s1, s1, 6
	s_lshr_b32 s21, s0, 5
	s_lshl_b32 s21, s21, 17
	s_add_u32 s1, s1, s21
	s_lshl_b32 s1, s1, 1
	s_add_u32 s1, s1, 0x4001000
	s_add_u32 s30, s68, s1
	s_addc_u32 s31, s69, 0
	s_movk_i32 s20, 0x800
	s_branch .Ltc1_d219

; #define LAS __attribute__((address_space(3)))
; __device__ __forceinline__ unsigned cvt_pk_bf16(float lo, float hi) { unsigned r; asm("v_cvt_pk_bf16_f32 %0, %1, %2" : "=v"(r) : "v"(lo), "v"(hi)); return r; }
; __device__ __forceinline__ int opaque_tid() { int t = threadIdx.x; asm volatile("" : "+v"(t)); return t; }
; __device__ __forceinline__ void tconv_tile(LAS float* tile, const float* src, int ld, int k0, int n0, int mode, bf16_t* dst, int K) {
;     ...
;     for (int it = 0; it < 2; ++it) { const int idx = tid + it * 512, kk = idx >> 4, n4 = (idx & 15) * 4, nn = n0 + n4; int oc = nn; bool valid = true;
;         if (mode == 1) { if (nn < 7680) oc = nn; else if (nn < 18944) oc = nn + 48; else if (nn < INW) oc = 7680 + (nn - 18944); else valid = false; }
;         f32x4 v = (f32x4){0.f, 0.f, 0.f, 0.f}; if (valid) v = *(const f32x4*)(src + (size_t)(k0 + kk) * ld + oc);
;         tile[kk * 65 + n4 + 0] = v[0]; tile[kk * 65 + n4 + 1] = v[1]; tile[kk * 65 + n4 + 2] = v[2]; tile[kk * 65 + n4 + 3] = v[3]; }
;     __syncthreads();
;     { const int n = tid >> 3, k8 = (tid & 7) * 8; float v[8];
; #pragma unroll
;         for (int e = 0; e < 8; ++e) v[e] = tile[(k8 + e) * 65 + n];
;         u32x4 w; w.x = cvt_pk_bf16(v[0], v[1]); w.y = cvt_pk_bf16(v[2], v[3]); w.z = cvt_pk_bf16(v[4], v[5]); w.w = cvt_pk_bf16(v[6], v[7]);
;         *(u32x4*)(dst + (size_t)(n0 + n) * K + k0 + k8) = w; }
;     __syncthreads();
; }
; __device__ __forceinline__ void prologue(LAS unsigned char* lds, const Ctx& P, int l) {
;     unsigned char* ws = P.ws; LAS float* tile = (LAS float*)lds;
;     const int tid = opaque_tid(), G = gridDim.x;
;     const int T_IN = 32 * 300, T_BR = 4 * 512, T_OUT = 1024, T_MEM = 1024, T_W1 = 256, T_WA = 64;
;     const int T_ALL = T_IN + T_BR + T_OUT + T_MEM + T_W1 + T_WA;
;     for (int t = blockIdx.x; t < T_ALL; t += G) {
;         int q = t;
;         if (q < T_IN) { const int kt = q & 31, ntl = q >> 5; tconv_tile(tile, P.in[3] + (size_t)l * DM * INW, INW, kt * 64, ntl * 64, 1, (bf16_t*)(ws + WS_WIN), DM); continue; }
.Ltc1_d226:
	v_mov_b32_e32 v42, 0
	v_mov_b32_e32 v43, 0
	v_mov_b32_e32 v44, 0
	v_mov_b32_e32 v45, 0
	v_mov_b32_e32 v46, 0
	v_mov_b32_e32 v47, 0
	v_mov_b32_e32 v48, 0
	v_mov_b32_e32 v49, 0
	v_mul_u32_u24_e32 v26, s28, v20
	v_add_lshl_u32 v26, v26, v21, 2
	s_lshl_b32 s0, s28, 7
	v_add_u32_e32 v27, s0, v26
	v_cmp_gt_i32_e32 vcc, s29, v21
	s_and_saveexec_b64 s[0:1], vcc
	global_load_dwordx4 v[42:45], v26, s[26:27]
	global_load_dwordx4 v[46:49], v27, s[26:27]
	s_mov_b64 exec, s[0:1]
	s_add_u32 s24, s24, s34
	s_sub_u32 s1, s24, 9600
	s_cmpk_lt_u32 s1, 3072
	s_cselect_b32 s1, 3072, 0
	s_add_u32 s24, s24, s1
	s_cmpk_ge_u32 s25, 14016
	s_cbranch_scc1 .Ltc1_exit
	s_waitcnt vmcnt(15)
	v_add_u32_e32 v28, 0, v22
	ds_write2_b32 v28, v50, v51 offset1:1
	ds_write2_b32 v28, v52, v53 offset0:2 offset1:3
	v_add_u32_e32 v28, 0x2080, v28
	ds_write2_b32 v28, v54, v55 offset1:1
	ds_write2_b32 v28, v56, v57 offset0:2 offset1:3
	s_mov_b32 s21, s25
	s_mov_b32 s0, s21
	s_cmpk_lt_u32 s0, 9600
	s_cbranch_scc0 .Ltc1_c240
	s_and_b32 s1, s0, 31
	s_lshl_b32 s1, s1, 6
	s_lshr_b32 s21, s0, 5
	s_lshl_b32 s21, s21, 17
	s_add_u32 s1, s1, s21
	s_lshl_b32 s1, s1, 1
	s_add_u32 s1, s1, 0x4001000
	s_add_u32 s30, s68, s1
	s_addc_u32 s31, s69, 0
	s_movk_i32 s20, 0x800
	s_branch .Ltc1_d239

; #define LAS __attribute__((address_space(3)))
; __device__ __forceinline__ unsigned cvt_pk_bf16(float lo, float hi) { unsigned r; asm("v_cvt_pk_bf16_f32 %0, %1, %2" : "=v"(r) : "v"(lo), "v"(hi)); return r; }
; __device__ __forceinline__ int opaque_tid() { int t = threadIdx.x; asm volatile("" : "+v"(t)); return t; }
; __device__ __forceinline__ void tconv_tile(LAS float* tile, const float* src, int ld, int k0, int n0, int mode, bf16_t* dst, int K) {
;     ...
;     for (int it = 0; it < 2; ++it) { const int idx = tid + it * 512, kk = idx >> 4, n4 = (idx & 15) * 4, nn = n0 + n4; int oc = nn; bool valid = true;
;         if (mode == 1) { if (nn < 7680) oc = nn; else if (nn < 18944) oc = nn + 48; else if (nn < INW) oc = 7680 + (nn - 18944); else valid = false; }
;         f32x4 v = (f32x4){0.f, 0.f, 0.f, 0.f}; if (valid) v = *(const f32x4*)(src + (size_t)(k0 + kk) * ld + oc);
;         tile[kk * 65 + n4 + 0] = v[0]; tile[kk * 65 + n4 + 1] = v[1]; tile[kk * 65 + n4 + 2] = v[2]; tile[kk * 65 + n4 + 3] = v[3]; }
;     __syncthreads();
;     { const int n = tid >> 3, k8 = (tid & 7) * 8; float v[8];
; #pragma unroll
;         for (int e = 0; e < 8; ++e) v[e] = tile[(k8 + e) * 65 + n];
;         u32x4 w; w.x = cvt_pk_bf16(v[0], v[1]); w.y = cvt_pk_bf16(v[2], v[3]); w.z = cvt_pk_bf16(v[4], v[5]); w.w = cvt_pk_bf16(v[6], v[7]);
;         *(u32x4*)(dst + (size_t)(n0 + n) * K + k0 + k8) = w; }
;     __syncthreads();
; }
; __device__ __forceinline__ void prologue(LAS unsigned char* lds, const Ctx& P, int l) {
;     unsigned char* ws = P.ws; LAS float* tile = (LAS float*)lds;
;     const int tid = opaque_tid(), G = gridDim.x;
;     const int T_IN = 32 * 300, T_BR = 4 * 512, T_OUT = 1024, T_MEM = 1024, T_W1 = 256, T_WA = 64;
;     const int T_ALL = T_IN + T_BR + T_OUT + T_MEM + T_W1 + T_WA;
;     for (int t = blockIdx.x; t < T_ALL; t += G) {
;         int q = t;
;         if (q < T_IN) { const int kt = q & 31, ntl = q >> 5; tconv_tile(tile, P.in[3] + (size_t)l * DM * INW, INW, kt * 64, ntl * 64, 1, (bf16_t*)(ws + WS_WIN), DM); continue; }
.Ltc1_d246:
	v_mov_b32_e32 v50, 0
	v_mov_b32_e32 v51, 0
	v_mov_b32_e32 v52, 0
	v_mov_b32_e32 v53, 0
	v_mov_b32_e32 v54, 0
	v_mov_b32_e32 v55, 0
	v_mov_b32_e32 v56, 0
	v_mov_b32_e32 v57, 0
	v_mul_u32_u24_e32 v26, s28, v20
	v_add_lshl_u32 v26, v26, v21, 2
	s_lshl_b32 s0, s28, 7
	v_add_u32_e32 v27, s0, v26
	v_cmp_gt_i32_e32 vcc, s29, v21
	s_and_saveexec_b64 s[0:1], vcc
	global_load_dwordx4 v[50:53], v26, s[26:27]
	global_load_dwordx4 v[54:57], v27, s[26:27]
	s_mov_b64 exec, s[0:1]
	s_add_u32 s24, s24, s34
	s_sub_u32 s1, s24, 9600
	s_cmpk_lt_u32 s1, 3072
	s_cselect_b32 s1, 3072, 0
	s_add_u32 s24, s24, s1
	s_cmpk_ge_u32 s25, 14016
	s_cbranch_scc1 .Ltc1_exit
	s_waitcnt vmcnt(15)
	v_add_u32_e32 v28, 16896, v22
	ds_write2_b32 v28, v58, v59 offset1:1
	ds_write2_b32 v28, v60, v61 offset0:2 offset1:3
	v_add_u32_e32 v28, 0x2080, v28
	ds_write2_b32 v28, v62, v63 offset1:1
	ds_write2_b32 v28, v64, v65 offset0:2 offset1:3
	s_mov_b32 s21, s25
	s_mov_b32 s0, s21
	s_cmpk_lt_u32 s0, 9600
	s_cbranch_scc0 .Ltc1_c260
	s_and_b32 s1, s0, 31
	s_lshl_b32 s1, s1, 6
	s_lshr_b32 s21, s0, 5
	s_lshl_b32 s21, s21, 17
	s_add_u32 s1, s1, s21
	s_lshl_b32 s1, s1, 1
	s_add_u32 s1, s1, 0x4001000
	s_add_u32 s30, s68, s1
	s_addc_u32 s31, s69, 0
	s_movk_i32 s20, 0x800
	s_branch .Ltc1_d259

; #define LAS __attribute__((address_space(3)))
; __device__ __forceinline__ unsigned cvt_pk_bf16(float lo, float hi) { unsigned r; asm("v_cvt_pk_bf16_f32 %0, %1, %2" : "=v"(r) : "v"(lo), "v"(hi)); return r; }
; __device__ __forceinline__ int opaque_tid() { int t = threadIdx.x; asm volatile("" : "+v"(t)); return t; }
; __device__ __forceinline__ void tconv_tile(LAS float* tile, const float* src, int ld, int k0, int n0, int mode, bf16_t* dst, int K) {
;     ...
;     for (int it = 0; it < 2; ++it) { const int idx = tid + it * 512, kk = idx >> 4, n4 = (idx & 15) * 4, nn = n0 + n4; int oc = nn; bool valid = true;
;         if (mode == 1) { if (nn < 7680) oc = nn; else if (nn < 18944) oc = nn + 48; else if (nn < INW) oc = 7680 + (nn - 18944); else valid = false; }
;         f32x4 v = (f32x4){0.f, 0.f, 0.f, 0.f}; if (valid) v = *(const f32x4*)(src + (size_t)(k0 + kk) * ld + oc);
;         tile[kk * 65 + n4 + 0] = v[0]; tile[kk * 65 + n4 + 1] = v[1]; tile[kk * 65 + n4 + 2] = v[2]; tile[kk * 65 + n4 + 3] = v[3]; }
;     __syncthreads();
;     { const int n = tid >> 3, k8 = (tid & 7) * 8; float v[8];
; #pragma unroll
;         for (int e = 0; e < 8; ++e) v[e] = tile[(k8 + e) * 65 + n];
;         u32x4 w; w.x = cvt_pk_bf16(v[0], v[1]); w.y = cvt_pk_bf16(v[2], v[3]); w.z = cvt_pk_bf16(v[4], v[5]); w.w = cvt_pk_bf16(v[6], v[7]);
;         *(u32x4*)(dst + (size_t)(n0 + n) * K + k0 + k8) = w; }
;     __syncthreads();
; }
; __device__ __forceinline__ void prologue(LAS unsigned char* lds, const Ctx& P, int l) {
;     unsigned char* ws = P.ws; LAS float* tile = (LAS float*)lds;
;     const int tid = opaque_tid(), G = gridDim.x;
;     const int T_IN = 32 * 300, T_BR = 4 * 512, T_OUT = 1024, T_MEM = 1024, T_W1 = 256, T_WA = 64;
;     const int T_ALL = T_IN + T_BR + T_OUT + T_MEM + T_W1 + T_WA;
;     for (int t = blockIdx.x; t < T_ALL; t += G) {
;         int q = t;
;         if (q < T_IN) { const int kt = q & 31, ntl = q >> 5; tconv_tile(tile, P.in[3] + (size_t)l * DM * INW, INW, kt * 64, ntl * 64, 1, (bf16_t*)(ws + WS_WIN), DM); continue; }
.Ltc1_d266:
	v_mov_b32_e32 v58, 0
	v_mov_b32_e32 v59, 0
	v_mov_b32_e32 v60, 0
	v_mov_b32_e32 v61, 0
	v_mov_b32_e32 v62, 0
	v_mov_b32_e32 v63, 0
	v_mov_b32_e32 v64, 0
	v_mov_b32_e32 v65, 0
	v_mul_u32_u24_e32 v26, s28, v20
	v_add_lshl_u32 v26, v26, v21, 2
	s_lshl_b32 s0, s28, 7
	v_add_u32_e32 v27, s0, v26
	v_cmp_gt_i32_e32 vcc, s29, v21
	s_and_saveexec_b64 s[0:1], vcc
	global_load_dwordx4 v[58:61], v26, s[26:27]
	global_load_dwordx4 v[62:65], v27, s[26:27]
	s_mov_b64 exec, s[0:1]
	s_add_u32 s24, s24, s34
	s_sub_u32 s1, s24, 9600
	s_cmpk_lt_u32 s1, 3072
	s_cselect_b32 s1, 3072, 0
	s_add_u32 s24, s24, s1
	s_cmpk_ge_u32 s25, 14016
	s_cbranch_scc1 .Ltc1_exit
	s_waitcnt vmcnt(15)
	v_add_u32_e32 v28, 0, v22
	ds_write2_b32 v28, v78, v79 offset1:1
	ds_write2_b32 v28, v80, v81 offset0:2 offset1:3
	v_add_u32_e32 v28, 0x2080, v28
	ds_write2_b32 v28, v82, v83 offset1:1
	ds_write2_b32 v28, v84, v85 offset0:2 offset1:3
	s_mov_b32 s21, s25
	s_mov_b32 s0, s21
	s_cmpk_lt_u32 s0, 9600
	s_cbranch_scc0 .Ltc1_c280
	s_and_b32 s1, s0, 31
	s_lshl_b32 s1, s1, 6
	s_lshr_b32 s21, s0, 5
	s_lshl_b32 s21, s21, 17
	s_add_u32 s1, s1, s21
	s_lshl_b32 s1, s1, 1
	s_add_u32 s1, s1, 0x4001000
	s_add_u32 s30, s68, s1
	s_addc_u32 s31, s69, 0
	s_movk_i32 s20, 0x800
	s_branch .Ltc1_d279

; __device__ __forceinline__ void tconv_tile(LAS float* tile, const float* src, int ld, int k0, int n0, int mode, bf16_t* dst, int K) {
;     ...
;     for (int it = 0; it < 2; ++it) { const int idx = tid + it * 512, kk = idx >> 4, n4 = (idx & 15) * 4, nn = n0 + n4; int oc = nn; bool valid = true;
;         if (mode == 1) { if (nn < 7680) oc = nn; else if (nn < 18944) oc = nn + 48; else if (nn < INW) oc = 7680 + (nn - 18944); else valid = false; }
;         f32x4 v = (f32x4){0.f, 0.f, 0.f, 0.f}; if (valid) v = *(const f32x4*)(src + (size_t)(k0 + kk) * ld + oc);
; __device__ __forceinline__ void prologue(LAS unsigned char* lds, const Ctx& P, int l) {
;     ...
;     for (int t = blockIdx.x; t < T_ALL; t += G) {
.Ltc1_d306:
	v_mov_b32_e32 v86, 0
	v_mov_b32_e32 v87, 0
	v_mov_b32_e32 v88, 0
	v_mov_b32_e32 v89, 0
	v_mov_b32_e32 v90, 0
	v_mov_b32_e32 v91, 0
	v_mov_b32_e32 v92, 0
	v_mov_b32_e32 v93, 0
	v_mul_u32_u24_e32 v26, s28, v20
	v_add_lshl_u32 v26, v26, v21, 2
	s_lshl_b32 s0, s28, 7
	v_add_u32_e32 v27, s0, v26
	v_cmp_gt_i32_e32 vcc, s29, v21
	s_and_saveexec_b64 s[0:1], vcc
	global_load_dwordx4 v[86:89], v26, s[26:27]
	global_load_dwordx4 v[90:93], v27, s[26:27]
	s_mov_b64 exec, s[0:1]
	s_add_u32 s24, s24, s34
	s_sub_u32 s1, s24, 9600
	s_cmpk_lt_u32 s1, 3072
	s_cselect_b32 s1, 3072, 0
	s_add_u32 s24, s24, s1
	s_branch .Ltc1_loop
